# GEMM K-loops: first 8 MFMAs of every MMA segment issued before the segment's barrier
# speedup vs baseline: 1.0181x; 1.0068x over previous
; #define PG8_STAGE(bufoff, gbase, voff) do { _Pragma("unroll") for (int _i = 0; _i < 2; ++_i) \
;         __builtin_amdgcn_global_load_lds((const unsigned*)((const char*)(gbase) + (voff)[_i]), (PG8_LAS unsigned*)(lds + (bufoff) + ldsw + _i * 8192), 16, 0, 0); } while (0)
; #define PG8_LDA(dst, b, h) do { _Pragma("unroll") for (int m = 0; m < 4; ++m) _Pragma("unroll") for (int k = 0; k < 2; ++k) dst[m][k] = *(const PG8_LAS bf16x8*)(lds + PG8_SA(b, h) + aoff + m * 2048 + k * 1024); } while (0)
; #define PG8_LDB(dst, b, h) do { _Pragma("unroll") for (int n = 0; n < 2; ++n) _Pragma("unroll") for (int k = 0; k < 2; ++k) dst[n][k] = *(const PG8_LAS bf16x8*)(lds + PG8_SB(b, h) + boff + n * 2048 + k * 1024); } while (0)
; #define PG8_MMA(ai, bj, At, Bt) do { __builtin_amdgcn_s_setprio(1); _Pragma("unroll") for (int m = 0; m < 4; ++m) _Pragma("unroll") for (int n = 0; n < 2; ++n) _Pragma("unroll") for (int k = 0; k < 2; ++k) \
;         acc[ai][bj][m][n] = __builtin_amdgcn_mfma_f32_16x16x32_bf16(Bt[n][k], At[m][k], acc[ai][bj][m][n], 0, 0, 0); __builtin_amdgcn_s_setprio(0); } while (0)
; #define PG8_WAIT_V(n) asm volatile("s_waitcnt vmcnt(" #n ")" ::: "memory")
; #define PG8_BAR __builtin_amdgcn_s_barrier()
; template <class Epi, class Sched, bool ALIGN_EPI = false, bool SP2 = false>
; __device__ __forceinline__ void gemm_phase(PG8_LAS unsigned char* lds, const Gemm g, const Sched& S, const Epi& E) {
;     ...
;         for (int t = 0; t < nt; t += 2) {
;             const bool last = (t == nt - 2);
;             const char* a1 = cA + (size_t)(t + 1) * kstep;
;             const char* a2 = last ? nA : cA + (size_t)(t + 2) * kstep; const char* b2 = last ? nB : cB + (size_t)(t + 2) * kstep;
;             const char* a3 = a2 + kstep; const char* b3 = b2 + kstep;
;             if (last && has_next) S.a_ready(nxt);
;             if constexpr (SP2) {
;             PG8_LDB(B0, 0, 0); PG8_LDB(B1, 0, 1); PG8_SCHED; PG8_LDA(At, 0, 0); PG8_STAGE(PG8_SA(1, 1), a1 + hstep, voffA);
;             PG8_WAIT_V(8); PG8_WAIT_L(0); PG8_BAR; PG8_MMA(0, 0, At, B0); PG8_MMA(0, 1, At, B1); PG8_BAR; PG8_SCHED;
;             PG8_LDA(At, 0, 1); PG8_STAGE(PG8_SB(0, 0), b2, voffB); PG8_STAGE(PG8_SB(0, 1), b2 + hstep, voffB); PG8_STAGE(PG8_SA(0, 0), a2, voffA);
;             PG8_WAIT_V(8); PG8_WAIT_L(0); PG8_BAR; PG8_MMA(1, 0, At, B0); PG8_MMA(1, 1, At, B1); PG8_BAR; PG8_SCHED;
.LBB0_102:
	ds_read_b128 v[146:149], v152
	ds_read_b128 v[156:159], v152 offset:1024
	ds_read_b128 v[160:163], v152 offset:2048
	ds_read_b128 v[164:167], v152 offset:3072
	ds_read_b128 v[172:175], v153
	ds_read_b128 v[176:179], v153 offset:1024
	ds_read_b128 v[180:183], v153 offset:2048
	ds_read_b128 v[184:187], v153 offset:3072
	s_add_u32 s2, s28, 0xfffc0080
	s_addc_u32 s3, s29, -1
	s_cmp_eq_u32 s46, 12
	s_cselect_b32 s17, s19, s3
	s_cselect_b32 s16, s44, s2
	s_cselect_b32 s3, s15, s31
	s_cselect_b32 s2, s45, s30
	v_lshl_add_u64 v[222:223], s[28:29], 0, v[138:139]
	s_add_i32 m0, s25, 0xc000
	ds_read_b128 v[188:191], v154
	ds_read_b128 v[192:195], v154 offset:1024
	ds_read_b128 v[198:201], v154 offset:2048
	ds_read_b128 v[202:205], v154 offset:3072
	ds_read_b128 v[206:209], v154 offset:4096
	ds_read_b128 v[210:213], v154 offset:5120
	ds_read_b128 v[214:217], v154 offset:6144
	ds_read_b128 v[218:221], v154 offset:7168
	global_load_lds_dwordx4 v[222:223], off
	v_lshl_add_u64 v[222:223], s[28:29], 0, v[140:141]
	s_add_i32 m0, s25, 0xe000
	s_nop 0
	global_load_lds_dwordx4 v[222:223], off
	s_waitcnt vmcnt(8)
	s_waitcnt lgkmcnt(0)
	v_mfma_f32_16x16x32_bf16 v[126:129], v[146:149], v[188:191], v[126:129]
	v_mfma_f32_16x16x32_bf16 v[118:121], v[160:163], v[188:191], v[118:121]
	v_mfma_f32_16x16x32_bf16 v[110:113], v[146:149], v[198:201], v[110:113]
	v_mfma_f32_16x16x32_bf16 v[102:105], v[160:163], v[198:201], v[102:105]
	v_mfma_f32_16x16x32_bf16 v[94:97], v[146:149], v[206:209], v[94:97]
	v_mfma_f32_16x16x32_bf16 v[86:89], v[160:163], v[206:209], v[86:89]
	v_mfma_f32_16x16x32_bf16 v[78:81], v[146:149], v[214:217], v[78:81]
	v_mfma_f32_16x16x32_bf16 v[70:73], v[160:163], v[214:217], v[70:73]
	s_barrier
	s_setprio 1
	s_waitcnt lgkmcnt(0)
	v_mfma_f32_16x16x32_bf16 v[126:129], v[156:159], v[192:195], v[126:129]
	v_mfma_f32_16x16x32_bf16 v[118:121], v[164:167], v[192:195], v[118:121]
	v_mfma_f32_16x16x32_bf16 v[110:113], v[156:159], v[202:205], v[110:113]
	v_mfma_f32_16x16x32_bf16 v[102:105], v[164:167], v[202:205], v[102:105]
	v_mfma_f32_16x16x32_bf16 v[94:97], v[156:159], v[210:213], v[94:97]
	v_mfma_f32_16x16x32_bf16 v[86:89], v[164:167], v[210:213], v[86:89]
	v_mfma_f32_16x16x32_bf16 v[78:81], v[156:159], v[218:221], v[78:81]
	v_mfma_f32_16x16x32_bf16 v[70:73], v[164:167], v[218:221], v[70:73]
	s_setprio 0
	s_setprio 1
	v_mfma_f32_16x16x32_bf16 v[122:125], v[172:175], v[188:191], v[122:125]
	v_mfma_f32_16x16x32_bf16 v[114:117], v[180:183], v[188:191], v[114:117]
	v_mfma_f32_16x16x32_bf16 v[106:109], v[172:175], v[198:201], v[106:109]
	v_mfma_f32_16x16x32_bf16 v[98:101], v[180:183], v[198:201], v[98:101]
	v_mfma_f32_16x16x32_bf16 v[90:93], v[172:175], v[206:209], v[90:93]
	v_mfma_f32_16x16x32_bf16 v[82:85], v[180:183], v[206:209], v[82:85]
	v_mfma_f32_16x16x32_bf16 v[74:77], v[172:175], v[214:217], v[74:77]
	v_mfma_f32_16x16x32_bf16 v[66:69], v[180:183], v[214:217], v[66:69]
	v_mfma_f32_16x16x32_bf16 v[122:125], v[176:179], v[192:195], v[122:125]
	v_mfma_f32_16x16x32_bf16 v[114:117], v[184:187], v[192:195], v[114:117]
	v_mfma_f32_16x16x32_bf16 v[106:109], v[176:179], v[202:205], v[106:109]
	v_mfma_f32_16x16x32_bf16 v[98:101], v[184:187], v[202:205], v[98:101]
	v_mfma_f32_16x16x32_bf16 v[90:93], v[176:179], v[210:213], v[90:93]
	v_mfma_f32_16x16x32_bf16 v[82:85], v[184:187], v[210:213], v[82:85]
	v_mfma_f32_16x16x32_bf16 v[74:77], v[176:179], v[218:221], v[74:77]
	v_mfma_f32_16x16x32_bf16 v[66:69], v[184:187], v[218:221], v[66:69]
	s_setprio 0
	s_barrier
	s_add_i32 s47, s40, s27
	v_lshl_add_u64 v[222:223], s[2:3], 0, v[132:133]
	s_mov_b32 m0, s47
	ds_read_b128 v[188:191], v154 offset:16384
	ds_read_b128 v[192:195], v154 offset:17408
	ds_read_b128 v[198:201], v154 offset:18432
	ds_read_b128 v[202:205], v154 offset:19456
	ds_read_b128 v[206:209], v154 offset:20480
	ds_read_b128 v[210:213], v154 offset:21504
	ds_read_b128 v[214:217], v154 offset:22528
	ds_read_b128 v[218:221], v154 offset:23552
	global_load_lds_dwordx4 v[222:223], off
	s_add_i32 m0, s47, 0x2000
	s_add_u32 s48, s2, 0x40000
	v_lshl_add_u64 v[224:225], s[2:3], 0, v[136:137]
	s_addc_u32 s49, s3, 0
	s_add_i32 s47, s41, s27
	global_load_lds_dwordx4 v[224:225], off
	v_lshl_add_u64 v[226:227], s[48:49], 0, v[132:133]
	s_mov_b32 m0, s47
	v_lshl_add_u64 v[228:229], s[16:17], 0, v[134:135]
	global_load_lds_dwordx4 v[226:227], off
	v_lshl_add_u64 v[226:227], s[48:49], 0, v[136:137]
	s_add_i32 m0, s47, 0x2000
	s_nop 0
	global_load_lds_dwordx4 v[226:227], off
	v_lshl_add_u64 v[226:227], s[16:17], 0, v[130:131]
	s_mov_b32 m0, s25
	s_nop 0
	global_load_lds_dwordx4 v[226:227], off
	s_mov_b32 m0, s33
	s_nop 0
	global_load_lds_dwordx4 v[228:229], off
	s_waitcnt vmcnt(8)
	s_waitcnt lgkmcnt(0)
	v_mfma_f32_16x16x32_bf16 v[62:65], v[146:149], v[188:191], v[62:65]
	v_mfma_f32_16x16x32_bf16 v[54:57], v[160:163], v[188:191], v[54:57]
	v_mfma_f32_16x16x32_bf16 v[46:49], v[146:149], v[198:201], v[46:49]
	v_mfma_f32_16x16x32_bf16 v[38:41], v[160:163], v[198:201], v[38:41]
	v_mfma_f32_16x16x32_bf16 v[30:33], v[146:149], v[206:209], v[30:33]
	v_mfma_f32_16x16x32_bf16 v[22:25], v[160:163], v[206:209], v[22:25]
	v_mfma_f32_16x16x32_bf16 v[14:17], v[146:149], v[214:217], v[14:17]
	v_mfma_f32_16x16x32_bf16 v[6:9], v[160:163], v[214:217], v[6:9]
	s_barrier
; #define PG8_STAGE(bufoff, gbase, voff) do { _Pragma("unroll") for (int _i = 0; _i < 2; ++_i) \
;         __builtin_amdgcn_global_load_lds((const unsigned*)((const char*)(gbase) + (voff)[_i]), (PG8_LAS unsigned*)(lds + (bufoff) + ldsw + _i * 8192), 16, 0, 0); } while (0)
; #define PG8_LDA(dst, b, h) do { _Pragma("unroll") for (int m = 0; m < 4; ++m) _Pragma("unroll") for (int k = 0; k < 2; ++k) dst[m][k] = *(const PG8_LAS bf16x8*)(lds + PG8_SA(b, h) + aoff + m * 2048 + k * 1024); } while (0)
; #define PG8_LDB(dst, b, h) do { _Pragma("unroll") for (int n = 0; n < 2; ++n) _Pragma("unroll") for (int k = 0; k < 2; ++k) dst[n][k] = *(const PG8_LAS bf16x8*)(lds + PG8_SB(b, h) + boff + n * 2048 + k * 1024); } while (0)
; #define PG8_MMA(ai, bj, At, Bt) do { __builtin_amdgcn_s_setprio(1); _Pragma("unroll") for (int m = 0; m < 4; ++m) _Pragma("unroll") for (int n = 0; n < 2; ++n) _Pragma("unroll") for (int k = 0; k < 2; ++k) \
;         acc[ai][bj][m][n] = __builtin_amdgcn_mfma_f32_16x16x32_bf16(Bt[n][k], At[m][k], acc[ai][bj][m][n], 0, 0, 0); __builtin_amdgcn_s_setprio(0); } while (0)
; #define PG8_WAIT_V(n) asm volatile("s_waitcnt vmcnt(" #n ")" ::: "memory")
; #define PG8_WAIT_L(n) asm volatile("s_waitcnt lgkmcnt(" #n ")" ::: "memory")
; #define PG8_BAR __builtin_amdgcn_s_barrier()
; #define PG8_SCHED __builtin_amdgcn_sched_barrier(0)
; template <class Epi, class Sched, bool ALIGN_EPI = false, bool SP2 = false>
; __device__ __forceinline__ void gemm_phase(PG8_LAS unsigned char* lds, const Gemm g, const Sched& S, const Epi& E) {
;     ...
;             PG8_WAIT_V(8); PG8_WAIT_L(0); PG8_BAR; PG8_MMA(1, 0, At, B0); PG8_MMA(1, 1, At, B1); PG8_BAR; PG8_SCHED;
;             PG8_LDB(B0, 1, 0); PG8_LDB(B1, 1, 1); PG8_SCHED; PG8_LDA(At, 1, 0); PG8_STAGE(PG8_SA(0, 1), a2 + hstep, voffA);
;             PG8_WAIT_V(8); PG8_WAIT_L(0); PG8_BAR; PG8_MMA(0, 0, At, B0); PG8_MMA(0, 1, At, B1); PG8_BAR; PG8_SCHED;
	s_setprio 1
	s_waitcnt lgkmcnt(0)
	v_mfma_f32_16x16x32_bf16 v[62:65], v[156:159], v[192:195], v[62:65]
	v_mfma_f32_16x16x32_bf16 v[54:57], v[164:167], v[192:195], v[54:57]
	v_mfma_f32_16x16x32_bf16 v[46:49], v[156:159], v[202:205], v[46:49]
	v_mfma_f32_16x16x32_bf16 v[38:41], v[164:167], v[202:205], v[38:41]
	v_mfma_f32_16x16x32_bf16 v[30:33], v[156:159], v[210:213], v[30:33]
	v_mfma_f32_16x16x32_bf16 v[22:25], v[164:167], v[210:213], v[22:25]
	v_mfma_f32_16x16x32_bf16 v[14:17], v[156:159], v[218:221], v[14:17]
	v_mfma_f32_16x16x32_bf16 v[6:9], v[164:167], v[218:221], v[6:9]
	s_setprio 0
	s_setprio 1
	v_mfma_f32_16x16x32_bf16 v[58:61], v[172:175], v[188:191], v[58:61]
	v_mfma_f32_16x16x32_bf16 v[50:53], v[180:183], v[188:191], v[50:53]
	v_mfma_f32_16x16x32_bf16 v[42:45], v[172:175], v[198:201], v[42:45]
	v_mfma_f32_16x16x32_bf16 v[34:37], v[180:183], v[198:201], v[34:37]
	v_mfma_f32_16x16x32_bf16 v[26:29], v[172:175], v[206:209], v[26:29]
	v_mfma_f32_16x16x32_bf16 v[18:21], v[180:183], v[206:209], v[18:21]
	v_mfma_f32_16x16x32_bf16 v[10:13], v[172:175], v[214:217], v[10:13]
	v_mfma_f32_16x16x32_bf16 v[2:5], v[180:183], v[214:217], v[2:5]
	v_mfma_f32_16x16x32_bf16 v[58:61], v[176:179], v[192:195], v[58:61]
	v_mfma_f32_16x16x32_bf16 v[50:53], v[184:187], v[192:195], v[50:53]
	v_mfma_f32_16x16x32_bf16 v[42:45], v[176:179], v[202:205], v[42:45]
	v_mfma_f32_16x16x32_bf16 v[34:37], v[184:187], v[202:205], v[34:37]
	v_mfma_f32_16x16x32_bf16 v[26:29], v[176:179], v[210:213], v[26:29]
	v_mfma_f32_16x16x32_bf16 v[18:21], v[184:187], v[210:213], v[18:21]
	v_mfma_f32_16x16x32_bf16 v[10:13], v[176:179], v[218:221], v[10:13]
	v_mfma_f32_16x16x32_bf16 v[2:5], v[184:187], v[218:221], v[2:5]
	s_setprio 0
	s_barrier
	s_add_i32 s47, 0, 0x18000
	v_add_u32_e32 v155, s47, v150
	s_add_i32 s48, 0, 0x1c000
	ds_read_b128 v[146:149], v155
	ds_read_b128 v[156:159], v155 offset:1024
	ds_read_b128 v[160:163], v155 offset:2048
	ds_read_b128 v[164:167], v155 offset:3072
	v_add_u32_e32 v155, s48, v150
	ds_read_b128 v[172:175], v155
	ds_read_b128 v[176:179], v155 offset:1024
	ds_read_b128 v[180:183], v155 offset:2048
	ds_read_b128 v[184:187], v155 offset:3072
	s_add_u32 s16, s16, 0x40000
	s_addc_u32 s17, s17, 0
	s_mov_b32 m0, s34
	v_lshl_add_u64 v[230:231], s[16:17], 0, v[130:131]
	ds_read_b128 v[188:191], v154 offset:32768
	ds_read_b128 v[192:195], v154 offset:33792
	ds_read_b128 v[198:201], v154 offset:34816
	ds_read_b128 v[202:205], v154 offset:35840
	ds_read_b128 v[206:209], v154 offset:36864
	ds_read_b128 v[210:213], v154 offset:37888
	ds_read_b128 v[214:217], v154 offset:38912
	ds_read_b128 v[218:221], v154 offset:39936
	global_load_lds_dwordx4 v[230:231], off
	v_lshl_add_u64 v[230:231], s[16:17], 0, v[134:135]
	s_mov_b32 m0, s35
	s_nop 0
	global_load_lds_dwordx4 v[230:231], off
	s_waitcnt vmcnt(8)
	s_waitcnt lgkmcnt(0)
	v_mfma_f32_16x16x32_bf16 v[126:129], v[146:149], v[188:191], v[126:129]
	v_mfma_f32_16x16x32_bf16 v[118:121], v[160:163], v[188:191], v[118:121]
	v_mfma_f32_16x16x32_bf16 v[110:113], v[146:149], v[198:201], v[110:113]
	v_mfma_f32_16x16x32_bf16 v[102:105], v[160:163], v[198:201], v[102:105]
	v_mfma_f32_16x16x32_bf16 v[94:97], v[146:149], v[206:209], v[94:97]
	v_mfma_f32_16x16x32_bf16 v[86:89], v[160:163], v[206:209], v[86:89]
	v_mfma_f32_16x16x32_bf16 v[78:81], v[146:149], v[214:217], v[78:81]
	v_mfma_f32_16x16x32_bf16 v[70:73], v[160:163], v[214:217], v[70:73]
	s_barrier
	s_setprio 1
	s_waitcnt lgkmcnt(0)
	v_mfma_f32_16x16x32_bf16 v[126:129], v[156:159], v[192:195], v[126:129]
	v_mfma_f32_16x16x32_bf16 v[118:121], v[164:167], v[192:195], v[118:121]
	v_mfma_f32_16x16x32_bf16 v[110:113], v[156:159], v[202:205], v[110:113]
	v_mfma_f32_16x16x32_bf16 v[102:105], v[164:167], v[202:205], v[102:105]
	v_mfma_f32_16x16x32_bf16 v[94:97], v[156:159], v[210:213], v[94:97]
	v_mfma_f32_16x16x32_bf16 v[86:89], v[164:167], v[210:213], v[86:89]
	v_mfma_f32_16x16x32_bf16 v[78:81], v[156:159], v[218:221], v[78:81]
	v_mfma_f32_16x16x32_bf16 v[70:73], v[164:167], v[218:221], v[70:73]
	s_setprio 0
	s_setprio 1
	v_mfma_f32_16x16x32_bf16 v[122:125], v[172:175], v[188:191], v[122:125]
	v_mfma_f32_16x16x32_bf16 v[114:117], v[180:183], v[188:191], v[114:117]
	v_mfma_f32_16x16x32_bf16 v[106:109], v[172:175], v[198:201], v[106:109]
	v_mfma_f32_16x16x32_bf16 v[98:101], v[180:183], v[198:201], v[98:101]
	v_mfma_f32_16x16x32_bf16 v[90:93], v[172:175], v[206:209], v[90:93]
	v_mfma_f32_16x16x32_bf16 v[82:85], v[180:183], v[206:209], v[82:85]
	v_mfma_f32_16x16x32_bf16 v[74:77], v[172:175], v[214:217], v[74:77]
	v_mfma_f32_16x16x32_bf16 v[66:69], v[180:183], v[214:217], v[66:69]
	v_mfma_f32_16x16x32_bf16 v[122:125], v[176:179], v[192:195], v[122:125]
	v_mfma_f32_16x16x32_bf16 v[114:117], v[184:187], v[192:195], v[114:117]
	v_mfma_f32_16x16x32_bf16 v[106:109], v[176:179], v[202:205], v[106:109]
	v_mfma_f32_16x16x32_bf16 v[98:101], v[184:187], v[202:205], v[98:101]
	v_mfma_f32_16x16x32_bf16 v[90:93], v[176:179], v[210:213], v[90:93]
	v_mfma_f32_16x16x32_bf16 v[82:85], v[184:187], v[210:213], v[82:85]
	v_mfma_f32_16x16x32_bf16 v[74:77], v[176:179], v[218:221], v[74:77]
	v_mfma_f32_16x16x32_bf16 v[66:69], v[184:187], v[218:221], v[66:69]
	s_setprio 0
	s_barrier
; #define PG8_STAGE(bufoff, gbase, voff) do { _Pragma("unroll") for (int _i = 0; _i < 2; ++_i) \
;         __builtin_amdgcn_global_load_lds((const unsigned*)((const char*)(gbase) + (voff)[_i]), (PG8_LAS unsigned*)(lds + (bufoff) + ldsw + _i * 8192), 16, 0, 0); } while (0)
; #define PG8_LDA(dst, b, h) do { _Pragma("unroll") for (int m = 0; m < 4; ++m) _Pragma("unroll") for (int k = 0; k < 2; ++k) dst[m][k] = *(const PG8_LAS bf16x8*)(lds + PG8_SA(b, h) + aoff + m * 2048 + k * 1024); } while (0)
; #define PG8_MMA(ai, bj, At, Bt) do { __builtin_amdgcn_s_setprio(1); _Pragma("unroll") for (int m = 0; m < 4; ++m) _Pragma("unroll") for (int n = 0; n < 2; ++n) _Pragma("unroll") for (int k = 0; k < 2; ++k) \
;         acc[ai][bj][m][n] = __builtin_amdgcn_mfma_f32_16x16x32_bf16(Bt[n][k], At[m][k], acc[ai][bj][m][n], 0, 0, 0); __builtin_amdgcn_s_setprio(0); } while (0)
; #define PG8_WAIT_V(n) asm volatile("s_waitcnt vmcnt(" #n ")" ::: "memory")
; #define PG8_WAIT_L(n) asm volatile("s_waitcnt lgkmcnt(" #n ")" ::: "memory")
; #define PG8_BAR __builtin_amdgcn_s_barrier()
; #define PG8_SCHED __builtin_amdgcn_sched_barrier(0)
; template <class Epi, class Sched, bool ALIGN_EPI = false, bool SP2 = false>
; __device__ __forceinline__ void gemm_phase(PG8_LAS unsigned char* lds, const Gemm g, const Sched& S, const Epi& E) {
;     ...
;             PG8_LDA(At, 1, 1); PG8_STAGE(PG8_SB(1, 0), b3, voffB); PG8_STAGE(PG8_SB(1, 1), b3 + hstep, voffB); PG8_STAGE(PG8_SA(1, 0), a3, voffA);
;             PG8_WAIT_V(8); PG8_WAIT_L(0); PG8_BAR; PG8_MMA(1, 0, At, B0); PG8_MMA(1, 1, At, B1); PG8_BAR; PG8_SCHED;
;     ...
;         if constexpr (ALIGN_EPI) { if (wr == 0) PG8_BAR; }
	s_add_i32 s16, s47, s27
	v_lshl_add_u64 v[222:223], v[222:223], 0, s[6:7]
	s_mov_b32 m0, s16
	ds_read_b128 v[188:191], v154 offset:49152
	ds_read_b128 v[192:195], v154 offset:50176
	ds_read_b128 v[198:201], v154 offset:51200
	ds_read_b128 v[202:205], v154 offset:52224
	ds_read_b128 v[206:209], v154 offset:53248
	ds_read_b128 v[210:213], v154 offset:54272
	ds_read_b128 v[214:217], v154 offset:55296
	ds_read_b128 v[218:221], v154 offset:56320
	global_load_lds_dwordx4 v[222:223], off
	s_add_i32 m0, s16, 0x2000
	s_add_u32 s2, s2, 0x40080
	v_lshl_add_u64 v[222:223], v[224:225], 0, s[6:7]
	s_addc_u32 s3, s3, 0
	s_add_i32 s16, s48, s27
	global_load_lds_dwordx4 v[222:223], off
	v_lshl_add_u64 v[222:223], s[2:3], 0, v[132:133]
	s_mov_b32 m0, s16
	s_nop 0
	global_load_lds_dwordx4 v[222:223], off
	v_lshl_add_u64 v[222:223], s[2:3], 0, v[136:137]
	s_add_i32 m0, s16, 0x2000
	s_nop 0
	global_load_lds_dwordx4 v[222:223], off
	v_lshl_add_u64 v[222:223], v[226:227], 0, s[6:7]
	s_mov_b32 m0, s37
	s_nop 0
	global_load_lds_dwordx4 v[222:223], off
	v_lshl_add_u64 v[222:223], v[228:229], 0, s[6:7]
	s_mov_b32 m0, s38
	s_nop 0
	global_load_lds_dwordx4 v[222:223], off
	s_waitcnt vmcnt(8)
	s_waitcnt lgkmcnt(0)
	v_mfma_f32_16x16x32_bf16 v[62:65], v[146:149], v[188:191], v[62:65]
	v_mfma_f32_16x16x32_bf16 v[54:57], v[160:163], v[188:191], v[54:57]
	v_mfma_f32_16x16x32_bf16 v[46:49], v[146:149], v[198:201], v[46:49]
	v_mfma_f32_16x16x32_bf16 v[38:41], v[160:163], v[198:201], v[38:41]
	v_mfma_f32_16x16x32_bf16 v[30:33], v[146:149], v[206:209], v[30:33]
	v_mfma_f32_16x16x32_bf16 v[22:25], v[160:163], v[206:209], v[22:25]
	v_mfma_f32_16x16x32_bf16 v[14:17], v[146:149], v[214:217], v[14:17]
	v_mfma_f32_16x16x32_bf16 v[6:9], v[160:163], v[214:217], v[6:9]
	s_barrier
	s_setprio 1
	s_waitcnt lgkmcnt(0)
	v_mfma_f32_16x16x32_bf16 v[62:65], v[156:159], v[192:195], v[62:65]
	v_mfma_f32_16x16x32_bf16 v[54:57], v[164:167], v[192:195], v[54:57]
	v_mfma_f32_16x16x32_bf16 v[46:49], v[156:159], v[202:205], v[46:49]
	v_mfma_f32_16x16x32_bf16 v[38:41], v[164:167], v[202:205], v[38:41]
	v_mfma_f32_16x16x32_bf16 v[30:33], v[156:159], v[210:213], v[30:33]
	v_mfma_f32_16x16x32_bf16 v[22:25], v[164:167], v[210:213], v[22:25]
	v_mfma_f32_16x16x32_bf16 v[14:17], v[156:159], v[218:221], v[14:17]
	v_mfma_f32_16x16x32_bf16 v[6:9], v[164:167], v[218:221], v[6:9]
	s_setprio 0
	s_setprio 1
	v_mfma_f32_16x16x32_bf16 v[58:61], v[172:175], v[188:191], v[58:61]
	v_mfma_f32_16x16x32_bf16 v[50:53], v[180:183], v[188:191], v[50:53]
	v_mfma_f32_16x16x32_bf16 v[42:45], v[172:175], v[198:201], v[42:45]
	v_mfma_f32_16x16x32_bf16 v[34:37], v[180:183], v[198:201], v[34:37]
	v_mfma_f32_16x16x32_bf16 v[26:29], v[172:175], v[206:209], v[26:29]
	v_mfma_f32_16x16x32_bf16 v[18:21], v[180:183], v[206:209], v[18:21]
	v_mfma_f32_16x16x32_bf16 v[10:13], v[172:175], v[214:217], v[10:13]
	v_mfma_f32_16x16x32_bf16 v[2:5], v[180:183], v[214:217], v[2:5]
	v_mfma_f32_16x16x32_bf16 v[58:61], v[176:179], v[192:195], v[58:61]
	v_mfma_f32_16x16x32_bf16 v[50:53], v[184:187], v[192:195], v[50:53]
	v_mfma_f32_16x16x32_bf16 v[42:45], v[176:179], v[202:205], v[42:45]
	v_mfma_f32_16x16x32_bf16 v[34:37], v[184:187], v[202:205], v[34:37]
	v_mfma_f32_16x16x32_bf16 v[26:29], v[176:179], v[210:213], v[26:29]
	v_mfma_f32_16x16x32_bf16 v[18:21], v[184:187], v[210:213], v[18:21]
	v_mfma_f32_16x16x32_bf16 v[10:13], v[176:179], v[218:221], v[10:13]
	v_mfma_f32_16x16x32_bf16 v[2:5], v[184:187], v[218:221], v[2:5]
	s_setprio 0
	s_barrier
	s_add_i32 s46, s46, 2
	s_add_u32 s28, s28, 0x100
	s_addc_u32 s29, s29, 0
	s_add_u32 s30, s30, 0x100
	s_addc_u32 s31, s31, 0
	s_cmp_gt_u32 s46, 13
	s_cbranch_scc0 .LBB0_102
	s_and_b64 vcc, exec, s[12:13]
	s_cbranch_vccz .LBB0_105
	s_barrier

; #define PG8_STAGE(bufoff, gbase, voff) do { _Pragma("unroll") for (int _i = 0; _i < 2; ++_i) \
;         __builtin_amdgcn_global_load_lds((const unsigned*)((const char*)(gbase) + (voff)[_i]), (PG8_LAS unsigned*)(lds + (bufoff) + ldsw + _i * 8192), 16, 0, 0); } while (0)
; #define PG8_LDA(dst, b, h) do { _Pragma("unroll") for (int m = 0; m < 4; ++m) _Pragma("unroll") for (int k = 0; k < 2; ++k) dst[m][k] = *(const PG8_LAS bf16x8*)(lds + PG8_SA(b, h) + aoff + m * 2048 + k * 1024); } while (0)
; #define PG8_LDB(dst, b, h) do { _Pragma("unroll") for (int n = 0; n < 2; ++n) _Pragma("unroll") for (int k = 0; k < 2; ++k) dst[n][k] = *(const PG8_LAS bf16x8*)(lds + PG8_SB(b, h) + boff + n * 2048 + k * 1024); } while (0)
; #define PG8_MMA(ai, bj, At, Bt) do { __builtin_amdgcn_s_setprio(1); _Pragma("unroll") for (int m = 0; m < 4; ++m) _Pragma("unroll") for (int n = 0; n < 2; ++n) _Pragma("unroll") for (int k = 0; k < 2; ++k) \
;         acc[ai][bj][m][n] = __builtin_amdgcn_mfma_f32_16x16x32_bf16(Bt[n][k], At[m][k], acc[ai][bj][m][n], 0, 0, 0); __builtin_amdgcn_s_setprio(0); } while (0)
; #define PG8_WAIT_V(n) asm volatile("s_waitcnt vmcnt(" #n ")" ::: "memory")
; #define PG8_BAR __builtin_amdgcn_s_barrier()
; template <class Epi, class Sched, bool ALIGN_EPI = false, bool SP2 = false>
; __device__ __forceinline__ void gemm_phase(PG8_LAS unsigned char* lds, const Gemm g, const Sched& S, const Epi& E) {
;     ...
;         for (int t = 0; t < nt; t += 2) {
;             const bool last = (t == nt - 2);
;             const char* a1 = cA + (size_t)(t + 1) * kstep;
;             const char* a2 = last ? nA : cA + (size_t)(t + 2) * kstep; const char* b2 = last ? nB : cB + (size_t)(t + 2) * kstep;
;             const char* a3 = a2 + kstep; const char* b3 = b2 + kstep;
;             if (last && has_next) S.a_ready(nxt);
;             if constexpr (SP2) {
;             PG8_LDB(B0, 0, 0); PG8_LDB(B1, 0, 1); PG8_SCHED; PG8_LDA(At, 0, 0); PG8_STAGE(PG8_SA(1, 1), a1 + hstep, voffA);
;             PG8_WAIT_V(8); PG8_WAIT_L(0); PG8_BAR; PG8_MMA(0, 0, At, B0); PG8_MMA(0, 1, At, B1); PG8_BAR; PG8_SCHED;
;             PG8_LDA(At, 0, 1); PG8_STAGE(PG8_SB(0, 0), b2, voffB); PG8_STAGE(PG8_SB(0, 1), b2 + hstep, voffB); PG8_STAGE(PG8_SA(0, 0), a2, voffA);
;             PG8_WAIT_V(8); PG8_WAIT_L(0); PG8_BAR; PG8_MMA(1, 0, At, B0); PG8_MMA(1, 1, At, B1); PG8_BAR; PG8_SCHED;
.LBB0_187:
	v_add_u32_e32 v155, s40, v153
	ds_read_b128 v[156:159], v155
	ds_read_b128 v[160:163], v155 offset:1024
	ds_read_b128 v[164:167], v155 offset:2048
	ds_read_b128 v[172:175], v155 offset:3072
	v_add_u32_e32 v155, s41, v153
	s_add_u32 s2, s12, s22
	ds_read_b128 v[176:179], v155
	ds_read_b128 v[180:183], v155 offset:1024
	ds_read_b128 v[184:187], v155 offset:2048
	ds_read_b128 v[188:191], v155 offset:3072
	s_addc_u32 s3, s13, s23
	s_add_u32 s2, s2, 0x100
	s_addc_u32 s3, s3, 0
	s_add_u32 s49, s45, s22
	s_addc_u32 s52, s46, s23
	s_cmpk_eq_i32 s22, 0x1500
	s_cselect_b32 s17, s21, s3
	s_cselect_b32 s16, s20, s2
	s_cselect_b32 s3, s1, s52
	s_cselect_b32 s2, s0, s49
	v_lshl_add_u64 v[226:227], v[148:149], 0, s[22:23]
	s_add_i32 m0, s30, 0xc000
	ds_read_b128 v[192:195], v154
	ds_read_b128 v[198:201], v154 offset:1024
	ds_read_b128 v[202:205], v154 offset:2048
	ds_read_b128 v[206:209], v154 offset:3072
	ds_read_b128 v[210:213], v154 offset:4096
	ds_read_b128 v[214:217], v154 offset:5120
	ds_read_b128 v[218:221], v154 offset:6144
	ds_read_b128 v[222:225], v154 offset:7168
	global_load_lds_dwordx4 v[226:227], off
	v_lshl_add_u64 v[226:227], v[150:151], 0, s[22:23]
	s_add_i32 m0, s30, 0xe000
	s_nop 0
	global_load_lds_dwordx4 v[226:227], off
	s_waitcnt vmcnt(8)
	s_waitcnt lgkmcnt(0)
	v_mfma_f32_16x16x32_bf16 v[112:115], v[156:159], v[192:195], v[112:115]
	v_mfma_f32_16x16x32_bf16 v[124:127], v[164:167], v[192:195], v[124:127]
	v_mfma_f32_16x16x32_bf16 v[96:99], v[156:159], v[202:205], v[96:99]
	v_mfma_f32_16x16x32_bf16 v[128:131], v[164:167], v[202:205], v[128:131]
	v_mfma_f32_16x16x32_bf16 v[100:103], v[156:159], v[210:213], v[100:103]
	v_mfma_f32_16x16x32_bf16 v[116:119], v[164:167], v[210:213], v[116:119]
	v_mfma_f32_16x16x32_bf16 v[104:107], v[156:159], v[218:221], v[104:107]
	v_mfma_f32_16x16x32_bf16 v[120:123], v[164:167], v[218:221], v[120:123]
	s_barrier
	s_setprio 1
	s_waitcnt lgkmcnt(0)
	v_mfma_f32_16x16x32_bf16 v[112:115], v[160:163], v[198:201], v[112:115]
	v_mfma_f32_16x16x32_bf16 v[124:127], v[172:175], v[198:201], v[124:127]
	v_mfma_f32_16x16x32_bf16 v[96:99], v[160:163], v[206:209], v[96:99]
	v_mfma_f32_16x16x32_bf16 v[128:131], v[172:175], v[206:209], v[128:131]
	v_mfma_f32_16x16x32_bf16 v[100:103], v[160:163], v[214:217], v[100:103]
	v_mfma_f32_16x16x32_bf16 v[116:119], v[172:175], v[214:217], v[116:119]
	v_mfma_f32_16x16x32_bf16 v[104:107], v[160:163], v[222:225], v[104:107]
	v_mfma_f32_16x16x32_bf16 v[120:123], v[172:175], v[222:225], v[120:123]
	s_setprio 0
	s_setprio 1
	v_mfma_f32_16x16x32_bf16 v[108:111], v[176:179], v[192:195], v[108:111]
	v_mfma_f32_16x16x32_bf16 v[92:95], v[184:187], v[192:195], v[92:95]
	v_mfma_f32_16x16x32_bf16 v[80:83], v[176:179], v[202:205], v[80:83]
	v_mfma_f32_16x16x32_bf16 v[68:71], v[184:187], v[202:205], v[68:71]
	v_mfma_f32_16x16x32_bf16 v[84:87], v[176:179], v[210:213], v[84:87]
	v_mfma_f32_16x16x32_bf16 v[72:75], v[184:187], v[210:213], v[72:75]
	v_mfma_f32_16x16x32_bf16 v[88:91], v[176:179], v[218:221], v[88:91]
	v_mfma_f32_16x16x32_bf16 v[76:79], v[184:187], v[218:221], v[76:79]
	v_mfma_f32_16x16x32_bf16 v[108:111], v[180:183], v[198:201], v[108:111]
	v_mfma_f32_16x16x32_bf16 v[92:95], v[188:191], v[198:201], v[92:95]
	v_mfma_f32_16x16x32_bf16 v[80:83], v[180:183], v[206:209], v[80:83]
	v_mfma_f32_16x16x32_bf16 v[68:71], v[188:191], v[206:209], v[68:71]
	v_mfma_f32_16x16x32_bf16 v[84:87], v[180:183], v[214:217], v[84:87]
	v_mfma_f32_16x16x32_bf16 v[72:75], v[188:191], v[214:217], v[72:75]
	v_mfma_f32_16x16x32_bf16 v[88:91], v[180:183], v[222:225], v[88:91]
	v_mfma_f32_16x16x32_bf16 v[76:79], v[188:191], v[222:225], v[76:79]
	s_setprio 0
	s_barrier
	s_add_i32 s49, s40, s29
	v_lshl_add_u64 v[226:227], s[2:3], 0, v[134:135]
	s_mov_b32 m0, s49
	ds_read_b128 v[192:195], v154 offset:16384
	ds_read_b128 v[198:201], v154 offset:17408
	ds_read_b128 v[202:205], v154 offset:18432
	ds_read_b128 v[206:209], v154 offset:19456
	ds_read_b128 v[210:213], v154 offset:20480
	ds_read_b128 v[214:217], v154 offset:21504
	ds_read_b128 v[218:221], v154 offset:22528
	ds_read_b128 v[222:225], v154 offset:23552
	global_load_lds_dwordx4 v[226:227], off
	s_add_i32 m0, s49, 0x2000
	s_add_u32 s52, s2, 0xb0000
	v_lshl_add_u64 v[228:229], s[2:3], 0, v[138:139]
	s_addc_u32 s53, s3, 0
	s_add_i32 s49, s41, s29
	global_load_lds_dwordx4 v[228:229], off
	v_lshl_add_u64 v[230:231], s[52:53], 0, v[134:135]
	s_mov_b32 m0, s49
	v_lshl_add_u64 v[232:233], s[16:17], 0, v[136:137]
	global_load_lds_dwordx4 v[230:231], off
	v_lshl_add_u64 v[230:231], s[52:53], 0, v[138:139]
	s_add_i32 m0, s49, 0x2000
	s_nop 0
	global_load_lds_dwordx4 v[230:231], off
	v_lshl_add_u64 v[230:231], s[16:17], 0, v[132:133]
	s_mov_b32 m0, s30
	s_nop 0
	global_load_lds_dwordx4 v[230:231], off
	s_mov_b32 m0, s31
	s_nop 0
	global_load_lds_dwordx4 v[232:233], off
	s_waitcnt vmcnt(8)
	s_waitcnt lgkmcnt(0)
	v_mfma_f32_16x16x32_bf16 v[64:67], v[156:159], v[192:195], v[64:67]
	v_mfma_f32_16x16x32_bf16 v[60:63], v[164:167], v[192:195], v[60:63]
	v_mfma_f32_16x16x32_bf16 v[48:51], v[156:159], v[202:205], v[48:51]
	v_mfma_f32_16x16x32_bf16 v[44:47], v[164:167], v[202:205], v[44:47]
	v_mfma_f32_16x16x32_bf16 v[32:35], v[156:159], v[210:213], v[32:35]
	v_mfma_f32_16x16x32_bf16 v[28:31], v[164:167], v[210:213], v[28:31]
	v_mfma_f32_16x16x32_bf16 v[16:19], v[156:159], v[218:221], v[16:19]
	v_mfma_f32_16x16x32_bf16 v[12:15], v[164:167], v[218:221], v[12:15]
	s_barrier
; #define PG8_STAGE(bufoff, gbase, voff) do { _Pragma("unroll") for (int _i = 0; _i < 2; ++_i) \
;         __builtin_amdgcn_global_load_lds((const unsigned*)((const char*)(gbase) + (voff)[_i]), (PG8_LAS unsigned*)(lds + (bufoff) + ldsw + _i * 8192), 16, 0, 0); } while (0)
; #define PG8_LDA(dst, b, h) do { _Pragma("unroll") for (int m = 0; m < 4; ++m) _Pragma("unroll") for (int k = 0; k < 2; ++k) dst[m][k] = *(const PG8_LAS bf16x8*)(lds + PG8_SA(b, h) + aoff + m * 2048 + k * 1024); } while (0)
; #define PG8_LDB(dst, b, h) do { _Pragma("unroll") for (int n = 0; n < 2; ++n) _Pragma("unroll") for (int k = 0; k < 2; ++k) dst[n][k] = *(const PG8_LAS bf16x8*)(lds + PG8_SB(b, h) + boff + n * 2048 + k * 1024); } while (0)
; #define PG8_MMA(ai, bj, At, Bt) do { __builtin_amdgcn_s_setprio(1); _Pragma("unroll") for (int m = 0; m < 4; ++m) _Pragma("unroll") for (int n = 0; n < 2; ++n) _Pragma("unroll") for (int k = 0; k < 2; ++k) \
;         acc[ai][bj][m][n] = __builtin_amdgcn_mfma_f32_16x16x32_bf16(Bt[n][k], At[m][k], acc[ai][bj][m][n], 0, 0, 0); __builtin_amdgcn_s_setprio(0); } while (0)
; #define PG8_WAIT_V(n) asm volatile("s_waitcnt vmcnt(" #n ")" ::: "memory")
; #define PG8_WAIT_L(n) asm volatile("s_waitcnt lgkmcnt(" #n ")" ::: "memory")
; #define PG8_BAR __builtin_amdgcn_s_barrier()
; #define PG8_SCHED __builtin_amdgcn_sched_barrier(0)
; template <class Epi, class Sched, bool ALIGN_EPI = false, bool SP2 = false>
; __device__ __forceinline__ void gemm_phase(PG8_LAS unsigned char* lds, const Gemm g, const Sched& S, const Epi& E) {
;     ...
;             PG8_WAIT_V(8); PG8_WAIT_L(0); PG8_BAR; PG8_MMA(1, 0, At, B0); PG8_MMA(1, 1, At, B1); PG8_BAR; PG8_SCHED;
;             PG8_LDB(B0, 1, 0); PG8_LDB(B1, 1, 1); PG8_SCHED; PG8_LDA(At, 1, 0); PG8_STAGE(PG8_SA(0, 1), a2 + hstep, voffA);
;             PG8_WAIT_V(8); PG8_WAIT_L(0); PG8_BAR; PG8_MMA(0, 0, At, B0); PG8_MMA(0, 1, At, B1); PG8_BAR; PG8_SCHED;
	s_setprio 1
	s_waitcnt lgkmcnt(0)
	v_mfma_f32_16x16x32_bf16 v[64:67], v[160:163], v[198:201], v[64:67]
	v_mfma_f32_16x16x32_bf16 v[60:63], v[172:175], v[198:201], v[60:63]
	v_mfma_f32_16x16x32_bf16 v[48:51], v[160:163], v[206:209], v[48:51]
	v_mfma_f32_16x16x32_bf16 v[44:47], v[172:175], v[206:209], v[44:47]
	v_mfma_f32_16x16x32_bf16 v[32:35], v[160:163], v[214:217], v[32:35]
	v_mfma_f32_16x16x32_bf16 v[28:31], v[172:175], v[214:217], v[28:31]
	v_mfma_f32_16x16x32_bf16 v[16:19], v[160:163], v[222:225], v[16:19]
	v_mfma_f32_16x16x32_bf16 v[12:15], v[172:175], v[222:225], v[12:15]
	s_setprio 0
	s_setprio 1
	v_mfma_f32_16x16x32_bf16 v[56:59], v[176:179], v[192:195], v[56:59]
	v_mfma_f32_16x16x32_bf16 v[52:55], v[184:187], v[192:195], v[52:55]
	v_mfma_f32_16x16x32_bf16 v[40:43], v[176:179], v[202:205], v[40:43]
	v_mfma_f32_16x16x32_bf16 v[36:39], v[184:187], v[202:205], v[36:39]
	v_mfma_f32_16x16x32_bf16 v[24:27], v[176:179], v[210:213], v[24:27]
	v_mfma_f32_16x16x32_bf16 v[20:23], v[184:187], v[210:213], v[20:23]
	v_mfma_f32_16x16x32_bf16 v[8:11], v[176:179], v[218:221], v[8:11]
	v_mfma_f32_16x16x32_bf16 v[4:7], v[184:187], v[218:221], v[4:7]
	v_mfma_f32_16x16x32_bf16 v[56:59], v[180:183], v[198:201], v[56:59]
	v_mfma_f32_16x16x32_bf16 v[52:55], v[188:191], v[198:201], v[52:55]
	v_mfma_f32_16x16x32_bf16 v[40:43], v[180:183], v[206:209], v[40:43]
	v_mfma_f32_16x16x32_bf16 v[36:39], v[188:191], v[206:209], v[36:39]
	v_mfma_f32_16x16x32_bf16 v[24:27], v[180:183], v[214:217], v[24:27]
	v_mfma_f32_16x16x32_bf16 v[20:23], v[188:191], v[214:217], v[20:23]
	v_mfma_f32_16x16x32_bf16 v[8:11], v[180:183], v[222:225], v[8:11]
	v_mfma_f32_16x16x32_bf16 v[4:7], v[188:191], v[222:225], v[4:7]
	s_setprio 0
	s_barrier
	s_add_i32 s49, 0, 0x18000
	v_add_u32_e32 v155, s49, v153
	s_add_i32 s52, 0, 0x1c000
	ds_read_b128 v[156:159], v155
	ds_read_b128 v[160:163], v155 offset:1024
	ds_read_b128 v[164:167], v155 offset:2048
	ds_read_b128 v[172:175], v155 offset:3072
	v_add_u32_e32 v155, s52, v153
	ds_read_b128 v[176:179], v155
	ds_read_b128 v[180:183], v155 offset:1024
	ds_read_b128 v[184:187], v155 offset:2048
	ds_read_b128 v[188:191], v155 offset:3072
	s_add_u32 s16, s16, 0xb0000
	s_addc_u32 s17, s17, 0
	s_mov_b32 m0, s34
	v_lshl_add_u64 v[234:235], s[16:17], 0, v[132:133]
	ds_read_b128 v[192:195], v154 offset:32768
	ds_read_b128 v[198:201], v154 offset:33792
	ds_read_b128 v[202:205], v154 offset:34816
	ds_read_b128 v[206:209], v154 offset:35840
	ds_read_b128 v[210:213], v154 offset:36864
	ds_read_b128 v[214:217], v154 offset:37888
	ds_read_b128 v[218:221], v154 offset:38912
	ds_read_b128 v[222:225], v154 offset:39936
	global_load_lds_dwordx4 v[234:235], off
	v_lshl_add_u64 v[234:235], s[16:17], 0, v[136:137]
	s_mov_b32 m0, s35
	s_nop 0
	global_load_lds_dwordx4 v[234:235], off
	s_waitcnt vmcnt(8)
	s_waitcnt lgkmcnt(0)
	v_mfma_f32_16x16x32_bf16 v[112:115], v[156:159], v[192:195], v[112:115]
	v_mfma_f32_16x16x32_bf16 v[124:127], v[164:167], v[192:195], v[124:127]
	v_mfma_f32_16x16x32_bf16 v[96:99], v[156:159], v[202:205], v[96:99]
	v_mfma_f32_16x16x32_bf16 v[128:131], v[164:167], v[202:205], v[128:131]
	v_mfma_f32_16x16x32_bf16 v[100:103], v[156:159], v[210:213], v[100:103]
	v_mfma_f32_16x16x32_bf16 v[116:119], v[164:167], v[210:213], v[116:119]
	v_mfma_f32_16x16x32_bf16 v[104:107], v[156:159], v[218:221], v[104:107]
	v_mfma_f32_16x16x32_bf16 v[120:123], v[164:167], v[218:221], v[120:123]
	s_barrier
	s_setprio 1
	s_waitcnt lgkmcnt(0)
	v_mfma_f32_16x16x32_bf16 v[112:115], v[160:163], v[198:201], v[112:115]
	v_mfma_f32_16x16x32_bf16 v[124:127], v[172:175], v[198:201], v[124:127]
	v_mfma_f32_16x16x32_bf16 v[96:99], v[160:163], v[206:209], v[96:99]
	v_mfma_f32_16x16x32_bf16 v[128:131], v[172:175], v[206:209], v[128:131]
	v_mfma_f32_16x16x32_bf16 v[100:103], v[160:163], v[214:217], v[100:103]
	v_mfma_f32_16x16x32_bf16 v[116:119], v[172:175], v[214:217], v[116:119]
	v_mfma_f32_16x16x32_bf16 v[104:107], v[160:163], v[222:225], v[104:107]
	v_mfma_f32_16x16x32_bf16 v[120:123], v[172:175], v[222:225], v[120:123]
	s_setprio 0
	s_setprio 1
	v_mfma_f32_16x16x32_bf16 v[108:111], v[176:179], v[192:195], v[108:111]
	v_mfma_f32_16x16x32_bf16 v[92:95], v[184:187], v[192:195], v[92:95]
	v_mfma_f32_16x16x32_bf16 v[80:83], v[176:179], v[202:205], v[80:83]
	v_mfma_f32_16x16x32_bf16 v[68:71], v[184:187], v[202:205], v[68:71]
	v_mfma_f32_16x16x32_bf16 v[84:87], v[176:179], v[210:213], v[84:87]
	v_mfma_f32_16x16x32_bf16 v[72:75], v[184:187], v[210:213], v[72:75]
	v_mfma_f32_16x16x32_bf16 v[88:91], v[176:179], v[218:221], v[88:91]
	v_mfma_f32_16x16x32_bf16 v[76:79], v[184:187], v[218:221], v[76:79]
	v_mfma_f32_16x16x32_bf16 v[108:111], v[180:183], v[198:201], v[108:111]
	v_mfma_f32_16x16x32_bf16 v[92:95], v[188:191], v[198:201], v[92:95]
	v_mfma_f32_16x16x32_bf16 v[80:83], v[180:183], v[206:209], v[80:83]
	v_mfma_f32_16x16x32_bf16 v[68:71], v[188:191], v[206:209], v[68:71]
	v_mfma_f32_16x16x32_bf16 v[84:87], v[180:183], v[214:217], v[84:87]
	v_mfma_f32_16x16x32_bf16 v[72:75], v[188:191], v[214:217], v[72:75]
	v_mfma_f32_16x16x32_bf16 v[88:91], v[180:183], v[222:225], v[88:91]
	v_mfma_f32_16x16x32_bf16 v[76:79], v[188:191], v[222:225], v[76:79]
	s_setprio 0
	s_barrier
; #define PG8_STAGE(bufoff, gbase, voff) do { _Pragma("unroll") for (int _i = 0; _i < 2; ++_i) \
;         __builtin_amdgcn_global_load_lds((const unsigned*)((const char*)(gbase) + (voff)[_i]), (PG8_LAS unsigned*)(lds + (bufoff) + ldsw + _i * 8192), 16, 0, 0); } while (0)
; #define PG8_LDA(dst, b, h) do { _Pragma("unroll") for (int m = 0; m < 4; ++m) _Pragma("unroll") for (int k = 0; k < 2; ++k) dst[m][k] = *(const PG8_LAS bf16x8*)(lds + PG8_SA(b, h) + aoff + m * 2048 + k * 1024); } while (0)
; #define PG8_MMA(ai, bj, At, Bt) do { __builtin_amdgcn_s_setprio(1); _Pragma("unroll") for (int m = 0; m < 4; ++m) _Pragma("unroll") for (int n = 0; n < 2; ++n) _Pragma("unroll") for (int k = 0; k < 2; ++k) \
;         acc[ai][bj][m][n] = __builtin_amdgcn_mfma_f32_16x16x32_bf16(Bt[n][k], At[m][k], acc[ai][bj][m][n], 0, 0, 0); __builtin_amdgcn_s_setprio(0); } while (0)
; #define PG8_WAIT_V(n) asm volatile("s_waitcnt vmcnt(" #n ")" ::: "memory")
; #define PG8_WAIT_L(n) asm volatile("s_waitcnt lgkmcnt(" #n ")" ::: "memory")
; #define PG8_BAR __builtin_amdgcn_s_barrier()
; #define PG8_SCHED __builtin_amdgcn_sched_barrier(0)
; template <class Epi, class Sched, bool ALIGN_EPI = false, bool SP2 = false>
; __device__ __forceinline__ void gemm_phase(PG8_LAS unsigned char* lds, const Gemm g, const Sched& S, const Epi& E) {
;     ...
;             PG8_LDA(At, 1, 1); PG8_STAGE(PG8_SB(1, 0), b3, voffB); PG8_STAGE(PG8_SB(1, 1), b3 + hstep, voffB); PG8_STAGE(PG8_SA(1, 0), a3, voffA);
;             PG8_WAIT_V(8); PG8_WAIT_L(0); PG8_BAR; PG8_MMA(1, 0, At, B0); PG8_MMA(1, 1, At, B1); PG8_BAR; PG8_SCHED;
;     ...
;         if (!has_next) break;
; #pragma unroll
;         for (int a = 0; a < 2; ++a)
; #pragma unroll
;             for (int b = 0; b < 2; ++b)
; #pragma unroll
;                 for (int m = 0; m < 4; ++m)
; #pragma unroll
;                     for (int n = 0; n < 2; ++n) acc[a][b][m][n] = (f32x4){0.f, 0.f, 0.f, 0.f};
	s_add_i32 s16, s49, s29
	v_lshl_add_u64 v[226:227], v[226:227], 0, s[14:15]
	s_mov_b32 m0, s16
	ds_read_b128 v[192:195], v154 offset:49152
	ds_read_b128 v[198:201], v154 offset:50176
	ds_read_b128 v[202:205], v154 offset:51200
	ds_read_b128 v[206:209], v154 offset:52224
	ds_read_b128 v[210:213], v154 offset:53248
	ds_read_b128 v[214:217], v154 offset:54272
	ds_read_b128 v[218:221], v154 offset:55296
	ds_read_b128 v[222:225], v154 offset:56320
	global_load_lds_dwordx4 v[226:227], off
	s_add_i32 m0, s16, 0x2000
	s_add_u32 s2, s2, 0xb0080
	v_lshl_add_u64 v[226:227], v[228:229], 0, s[14:15]
	s_addc_u32 s3, s3, 0
	s_add_i32 s16, s52, s29
	global_load_lds_dwordx4 v[226:227], off
	v_lshl_add_u64 v[226:227], s[2:3], 0, v[134:135]
	s_mov_b32 m0, s16
	s_nop 0
	global_load_lds_dwordx4 v[226:227], off
	v_lshl_add_u64 v[226:227], s[2:3], 0, v[138:139]
	s_add_i32 m0, s16, 0x2000
	s_nop 0
	global_load_lds_dwordx4 v[226:227], off
	v_lshl_add_u64 v[226:227], v[230:231], 0, s[14:15]
	s_mov_b32 m0, s38
	s_nop 0
	global_load_lds_dwordx4 v[226:227], off
	v_lshl_add_u64 v[226:227], v[232:233], 0, s[14:15]
	s_mov_b32 m0, s39
	s_nop 0
	global_load_lds_dwordx4 v[226:227], off
	s_waitcnt vmcnt(8)
	s_waitcnt lgkmcnt(0)
	v_mfma_f32_16x16x32_bf16 v[64:67], v[156:159], v[192:195], v[64:67]
	v_mfma_f32_16x16x32_bf16 v[60:63], v[164:167], v[192:195], v[60:63]
	v_mfma_f32_16x16x32_bf16 v[48:51], v[156:159], v[202:205], v[48:51]
	v_mfma_f32_16x16x32_bf16 v[44:47], v[164:167], v[202:205], v[44:47]
	v_mfma_f32_16x16x32_bf16 v[32:35], v[156:159], v[210:213], v[32:35]
	v_mfma_f32_16x16x32_bf16 v[28:31], v[164:167], v[210:213], v[28:31]
	v_mfma_f32_16x16x32_bf16 v[16:19], v[156:159], v[218:221], v[16:19]
	v_mfma_f32_16x16x32_bf16 v[12:15], v[164:167], v[218:221], v[12:15]
	s_barrier
	s_setprio 1
	s_waitcnt lgkmcnt(0)
	v_mfma_f32_16x16x32_bf16 v[64:67], v[160:163], v[198:201], v[64:67]
	v_mfma_f32_16x16x32_bf16 v[60:63], v[172:175], v[198:201], v[60:63]
	v_mfma_f32_16x16x32_bf16 v[48:51], v[160:163], v[206:209], v[48:51]
	v_mfma_f32_16x16x32_bf16 v[44:47], v[172:175], v[206:209], v[44:47]
	v_mfma_f32_16x16x32_bf16 v[32:35], v[160:163], v[214:217], v[32:35]
	v_mfma_f32_16x16x32_bf16 v[28:31], v[172:175], v[214:217], v[28:31]
	v_mfma_f32_16x16x32_bf16 v[16:19], v[160:163], v[222:225], v[16:19]
	v_mfma_f32_16x16x32_bf16 v[12:15], v[172:175], v[222:225], v[12:15]
	s_setprio 0
	s_setprio 1
	v_mfma_f32_16x16x32_bf16 v[56:59], v[176:179], v[192:195], v[56:59]
	v_mfma_f32_16x16x32_bf16 v[52:55], v[184:187], v[192:195], v[52:55]
	v_mfma_f32_16x16x32_bf16 v[40:43], v[176:179], v[202:205], v[40:43]
	v_mfma_f32_16x16x32_bf16 v[36:39], v[184:187], v[202:205], v[36:39]
	v_mfma_f32_16x16x32_bf16 v[24:27], v[176:179], v[210:213], v[24:27]
	v_mfma_f32_16x16x32_bf16 v[20:23], v[184:187], v[210:213], v[20:23]
	v_mfma_f32_16x16x32_bf16 v[8:11], v[176:179], v[218:221], v[8:11]
	v_mfma_f32_16x16x32_bf16 v[4:7], v[184:187], v[218:221], v[4:7]
	v_mfma_f32_16x16x32_bf16 v[56:59], v[180:183], v[198:201], v[56:59]
	v_mfma_f32_16x16x32_bf16 v[52:55], v[188:191], v[198:201], v[52:55]
	v_mfma_f32_16x16x32_bf16 v[40:43], v[180:183], v[206:209], v[40:43]
	v_mfma_f32_16x16x32_bf16 v[36:39], v[188:191], v[206:209], v[36:39]
	v_mfma_f32_16x16x32_bf16 v[24:27], v[180:183], v[214:217], v[24:27]
	v_mfma_f32_16x16x32_bf16 v[20:23], v[188:191], v[214:217], v[20:23]
	v_mfma_f32_16x16x32_bf16 v[8:11], v[180:183], v[222:225], v[8:11]
	v_mfma_f32_16x16x32_bf16 v[4:7], v[188:191], v[222:225], v[4:7]
	s_setprio 0
	s_barrier
	s_add_i32 s47, s47, 2
	s_add_u32 s22, s22, 0x100
	s_addc_u32 s23, s23, 0
	s_cmp_gt_u32 s47, 41
	s_cbranch_scc0 .LBB0_187
	s_add_u32 s2, s45, 0xffffff00
	s_addc_u32 s3, s46, -1
	s_and_b64 vcc, exec, s[6:7]
	s_cbranch_vccnz .LBB0_190
	v_mov_b32_e32 v4, 0
	s_mov_b32 s60, s42
	s_mov_b32 s25, s43
	s_mov_b64 s[12:13], s[20:21]
	s_mov_b32 s37, s44
	v_mov_b32_e32 v5, v4
	v_mov_b32_e32 v6, v4
	v_mov_b32_e32 v7, v4
	v_mov_b32_e32 v8, v4
	v_mov_b32_e32 v9, v4
	v_mov_b32_e32 v10, v4
	v_mov_b32_e32 v11, v4
	v_mov_b32_e32 v20, v4
	v_mov_b32_e32 v21, v4
	v_mov_b32_e32 v22, v4
	v_mov_b32_e32 v23, v4
	v_mov_b32_e32 v24, v4
	v_mov_b32_e32 v25, v4
	v_mov_b32_e32 v26, v4
	v_mov_b32_e32 v27, v4
	v_mov_b32_e32 v36, v4
	v_mov_b32_e32 v37, v4
	v_mov_b32_e32 v38, v4
	v_mov_b32_e32 v39, v4
	v_mov_b32_e32 v40, v4
	v_mov_b32_e32 v41, v4
	v_mov_b32_e32 v42, v4
	v_mov_b32_e32 v43, v4
	v_mov_b32_e32 v52, v4
	v_mov_b32_e32 v53, v4
	v_mov_b32_e32 v54, v4
	v_mov_b32_e32 v55, v4
	v_mov_b32_e32 v56, v4
	v_mov_b32_e32 v57, v4
	v_mov_b32_e32 v58, v4
	v_mov_b32_e32 v59, v4
	v_mov_b32_e32 v12, v4
	v_mov_b32_e32 v13, v4
	v_mov_b32_e32 v14, v4
	v_mov_b32_e32 v15, v4
	v_mov_b32_e32 v16, v4
	v_mov_b32_e32 v17, v4
	v_mov_b32_e32 v18, v4
	v_mov_b32_e32 v19, v4
	v_mov_b32_e32 v28, v4
	v_mov_b32_e32 v29, v4
	v_mov_b32_e32 v30, v4
	v_mov_b32_e32 v31, v4
	v_mov_b32_e32 v32, v4
	v_mov_b32_e32 v33, v4
	v_mov_b32_e32 v34, v4
	v_mov_b32_e32 v35, v4
	v_mov_b32_e32 v44, v4
	v_mov_b32_e32 v45, v4
	v_mov_b32_e32 v46, v4
	v_mov_b32_e32 v47, v4
	v_mov_b32_e32 v48, v4
	v_mov_b32_e32 v49, v4
	v_mov_b32_e32 v50, v4
	v_mov_b32_e32 v51, v4
	v_mov_b32_e32 v60, v4
	v_mov_b32_e32 v61, v4
	v_mov_b32_e32 v62, v4
	v_mov_b32_e32 v63, v4
	v_mov_b32_e32 v64, v4
	v_mov_b32_e32 v65, v4
	v_mov_b32_e32 v66, v4
	v_mov_b32_e32 v67, v4
	v_mov_b32_e32 v76, v4
	v_mov_b32_e32 v77, v4
	v_mov_b32_e32 v78, v4
	v_mov_b32_e32 v79, v4
	v_mov_b32_e32 v88, v4
	v_mov_b32_e32 v89, v4
	v_mov_b32_e32 v90, v4
	v_mov_b32_e32 v91, v4
	v_mov_b32_e32 v72, v4
	v_mov_b32_e32 v73, v4
	v_mov_b32_e32 v74, v4
	v_mov_b32_e32 v75, v4
	v_mov_b32_e32 v84, v4
	v_mov_b32_e32 v85, v4
	v_mov_b32_e32 v86, v4
	v_mov_b32_e32 v87, v4
	v_mov_b32_e32 v68, v4
	v_mov_b32_e32 v69, v4
	v_mov_b32_e32 v70, v4
	v_mov_b32_e32 v71, v4
	v_mov_b32_e32 v80, v4
	v_mov_b32_e32 v81, v4
	v_mov_b32_e32 v82, v4
	v_mov_b32_e32 v83, v4
	v_mov_b32_e32 v92, v4
	v_mov_b32_e32 v93, v4
	v_mov_b32_e32 v94, v4
	v_mov_b32_e32 v95, v4
	v_mov_b32_e32 v108, v4
	v_mov_b32_e32 v109, v4
	v_mov_b32_e32 v110, v4
	v_mov_b32_e32 v111, v4
	v_mov_b32_e32 v120, v4
	v_mov_b32_e32 v121, v4
	v_mov_b32_e32 v122, v4
	v_mov_b32_e32 v123, v4
	v_mov_b32_e32 v104, v4
	v_mov_b32_e32 v105, v4
	v_mov_b32_e32 v106, v4
	v_mov_b32_e32 v107, v4
	v_mov_b32_e32 v116, v4
	v_mov_b32_e32 v117, v4
	v_mov_b32_e32 v118, v4
	v_mov_b32_e32 v119, v4
	v_mov_b32_e32 v100, v4
	v_mov_b32_e32 v101, v4
	v_mov_b32_e32 v102, v4
	v_mov_b32_e32 v103, v4
	v_mov_b32_e32 v128, v4
	v_mov_b32_e32 v129, v4
	v_mov_b32_e32 v130, v4
	v_mov_b32_e32 v131, v4
	v_mov_b32_e32 v96, v4
	v_mov_b32_e32 v97, v4
	v_mov_b32_e32 v98, v4
	v_mov_b32_e32 v99, v4
	v_mov_b32_e32 v124, v4
	v_mov_b32_e32 v125, v4
	v_mov_b32_e32 v126, v4
	v_mov_b32_e32 v127, v4
	v_mov_b32_e32 v112, v4
	v_mov_b32_e32 v113, v4
	v_mov_b32_e32 v114, v4
	v_mov_b32_e32 v115, v4
	s_andn2_b64 vcc, exec, s[4:5]
	s_cbranch_vccnz .LBB0_191
	s_branch .LBB0_192

; #define PG8_STAGE(bufoff, gbase, voff) do { _Pragma("unroll") for (int _i = 0; _i < 2; ++_i) \
;         __builtin_amdgcn_global_load_lds((const unsigned*)((const char*)(gbase) + (voff)[_i]), (PG8_LAS unsigned*)(lds + (bufoff) + ldsw + _i * 8192), 16, 0, 0); } while (0)
; #define PG8_LDA(dst, b, h) do { _Pragma("unroll") for (int m = 0; m < 4; ++m) _Pragma("unroll") for (int k = 0; k < 2; ++k) dst[m][k] = *(const PG8_LAS bf16x8*)(lds + PG8_SA(b, h) + aoff + m * 2048 + k * 1024); } while (0)
; #define PG8_LDB(dst, b, h) do { _Pragma("unroll") for (int n = 0; n < 2; ++n) _Pragma("unroll") for (int k = 0; k < 2; ++k) dst[n][k] = *(const PG8_LAS bf16x8*)(lds + PG8_SB(b, h) + boff + n * 2048 + k * 1024); } while (0)
; #define PG8_MMA(ai, bj, At, Bt) do { __builtin_amdgcn_s_setprio(1); _Pragma("unroll") for (int m = 0; m < 4; ++m) _Pragma("unroll") for (int n = 0; n < 2; ++n) _Pragma("unroll") for (int k = 0; k < 2; ++k) \
;         acc[ai][bj][m][n] = __builtin_amdgcn_mfma_f32_16x16x32_bf16(Bt[n][k], At[m][k], acc[ai][bj][m][n], 0, 0, 0); __builtin_amdgcn_s_setprio(0); } while (0)
; #define PG8_WAIT_V(n) asm volatile("s_waitcnt vmcnt(" #n ")" ::: "memory")
; #define PG8_BAR __builtin_amdgcn_s_barrier()
; template <class Epi, class Sched, bool ALIGN_EPI = false, bool SP2 = false>
; __device__ __forceinline__ void gemm_phase(PG8_LAS unsigned char* lds, const Gemm g, const Sched& S, const Epi& E) {
;     ...
;         for (int t = 0; t < nt; t += 2) {
;             const bool last = (t == nt - 2);
;             const char* a1 = cA + (size_t)(t + 1) * kstep;
;             const char* a2 = last ? nA : cA + (size_t)(t + 2) * kstep; const char* b2 = last ? nB : cB + (size_t)(t + 2) * kstep;
;             const char* a3 = a2 + kstep; const char* b3 = b2 + kstep;
;             if (last && has_next) S.a_ready(nxt);
;             if constexpr (SP2) {
;             PG8_LDB(B0, 0, 0); PG8_LDB(B1, 0, 1); PG8_SCHED; PG8_LDA(At, 0, 0); PG8_STAGE(PG8_SA(1, 1), a1 + hstep, voffA);
;             PG8_WAIT_V(8); PG8_WAIT_L(0); PG8_BAR; PG8_MMA(0, 0, At, B0); PG8_MMA(0, 1, At, B1); PG8_BAR; PG8_SCHED;
;             PG8_LDA(At, 0, 1); PG8_STAGE(PG8_SB(0, 0), b2, voffB); PG8_STAGE(PG8_SB(0, 1), b2 + hstep, voffB); PG8_STAGE(PG8_SA(0, 0), a2, voffA);
;             PG8_WAIT_V(8); PG8_WAIT_L(0); PG8_BAR; PG8_MMA(1, 0, At, B0); PG8_MMA(1, 1, At, B1); PG8_BAR; PG8_SCHED;
.LBB0_334:
	ds_read_b128 v[148:151], v164
	ds_read_b128 v[152:155], v164 offset:1024
	ds_read_b128 v[156:159], v164 offset:2048
	ds_read_b128 v[172:175], v164 offset:3072
	ds_read_b128 v[176:179], v165
	ds_read_b128 v[180:183], v165 offset:1024
	ds_read_b128 v[184:187], v165 offset:2048
	ds_read_b128 v[188:191], v165 offset:3072
	s_add_u32 s2, s10, 0xfffc0080
	s_addc_u32 s3, s11, -1
	s_cmp_eq_u32 s37, 12
	s_cselect_b32 s13, s7, s3
	s_cselect_b32 s12, s9, s2
	s_cselect_b32 s3, s14, s36
	s_cselect_b32 s2, s15, s29
	v_lshl_add_u64 v[160:161], s[10:11], 0, v[140:141]
	s_add_i32 m0, s17, 0xc000
	ds_read_b128 v[192:195], v166
	ds_read_b128 v[198:201], v166 offset:1024
	ds_read_b128 v[202:205], v166 offset:2048
	ds_read_b128 v[206:209], v166 offset:3072
	ds_read_b128 v[210:213], v166 offset:4096
	ds_read_b128 v[214:217], v166 offset:5120
	ds_read_b128 v[218:221], v166 offset:6144
	ds_read_b128 v[222:225], v166 offset:7168
	global_load_lds_dwordx4 v[160:161], off
	v_lshl_add_u64 v[160:161], s[10:11], 0, v[142:143]
	s_add_i32 m0, s17, 0xe000
	s_nop 0
	global_load_lds_dwordx4 v[160:161], off
	s_waitcnt vmcnt(8)
	s_waitcnt lgkmcnt(0)
	v_mfma_f32_16x16x32_bf16 v[126:129], v[148:151], v[192:195], v[126:129]
	v_mfma_f32_16x16x32_bf16 v[122:125], v[156:159], v[192:195], v[122:125]
	v_mfma_f32_16x16x32_bf16 v[110:113], v[148:151], v[202:205], v[110:113]
	v_mfma_f32_16x16x32_bf16 v[106:109], v[156:159], v[202:205], v[106:109]
	v_mfma_f32_16x16x32_bf16 v[94:97], v[148:151], v[210:213], v[94:97]
	v_mfma_f32_16x16x32_bf16 v[90:93], v[156:159], v[210:213], v[90:93]
	v_mfma_f32_16x16x32_bf16 v[78:81], v[148:151], v[218:221], v[78:81]
	v_mfma_f32_16x16x32_bf16 v[74:77], v[156:159], v[218:221], v[74:77]
	s_barrier
	s_setprio 1
	s_waitcnt lgkmcnt(0)
	v_mfma_f32_16x16x32_bf16 v[126:129], v[152:155], v[198:201], v[126:129]
	v_mfma_f32_16x16x32_bf16 v[122:125], v[172:175], v[198:201], v[122:125]
	v_mfma_f32_16x16x32_bf16 v[110:113], v[152:155], v[206:209], v[110:113]
	v_mfma_f32_16x16x32_bf16 v[106:109], v[172:175], v[206:209], v[106:109]
	v_mfma_f32_16x16x32_bf16 v[94:97], v[152:155], v[214:217], v[94:97]
	v_mfma_f32_16x16x32_bf16 v[90:93], v[172:175], v[214:217], v[90:93]
	v_mfma_f32_16x16x32_bf16 v[78:81], v[152:155], v[222:225], v[78:81]
	v_mfma_f32_16x16x32_bf16 v[74:77], v[172:175], v[222:225], v[74:77]
	s_setprio 0
	s_setprio 1
	v_mfma_f32_16x16x32_bf16 v[118:121], v[176:179], v[192:195], v[118:121]
	v_mfma_f32_16x16x32_bf16 v[114:117], v[184:187], v[192:195], v[114:117]
	v_mfma_f32_16x16x32_bf16 v[102:105], v[176:179], v[202:205], v[102:105]
	v_mfma_f32_16x16x32_bf16 v[98:101], v[184:187], v[202:205], v[98:101]
	v_mfma_f32_16x16x32_bf16 v[86:89], v[176:179], v[210:213], v[86:89]
	v_mfma_f32_16x16x32_bf16 v[82:85], v[184:187], v[210:213], v[82:85]
	v_mfma_f32_16x16x32_bf16 v[70:73], v[176:179], v[218:221], v[70:73]
	v_mfma_f32_16x16x32_bf16 v[66:69], v[184:187], v[218:221], v[66:69]
	v_mfma_f32_16x16x32_bf16 v[118:121], v[180:183], v[198:201], v[118:121]
	v_mfma_f32_16x16x32_bf16 v[114:117], v[188:191], v[198:201], v[114:117]
	v_mfma_f32_16x16x32_bf16 v[102:105], v[180:183], v[206:209], v[102:105]
	v_mfma_f32_16x16x32_bf16 v[98:101], v[188:191], v[206:209], v[98:101]
	v_mfma_f32_16x16x32_bf16 v[86:89], v[180:183], v[214:217], v[86:89]
	v_mfma_f32_16x16x32_bf16 v[82:85], v[188:191], v[214:217], v[82:85]
	v_mfma_f32_16x16x32_bf16 v[70:73], v[180:183], v[222:225], v[70:73]
	v_mfma_f32_16x16x32_bf16 v[66:69], v[188:191], v[222:225], v[66:69]
	s_setprio 0
	s_barrier
	s_add_i32 s38, s44, s16
	v_lshl_add_u64 v[160:161], s[2:3], 0, v[132:133]
	s_mov_b32 m0, s38
	ds_read_b128 v[192:195], v166 offset:16384
	ds_read_b128 v[198:201], v166 offset:17408
	ds_read_b128 v[202:205], v166 offset:18432
	ds_read_b128 v[206:209], v166 offset:19456
	ds_read_b128 v[210:213], v166 offset:20480
	ds_read_b128 v[214:217], v166 offset:21504
	ds_read_b128 v[218:221], v166 offset:22528
	ds_read_b128 v[222:225], v166 offset:23552
	global_load_lds_dwordx4 v[160:161], off
	s_add_i32 m0, s38, 0x2000
	s_add_u32 s38, s2, 0x40000
	v_lshl_add_u64 v[226:227], s[2:3], 0, v[136:137]
	s_addc_u32 s39, s3, 0
	s_add_i32 s40, s45, s16
	global_load_lds_dwordx4 v[226:227], off
	v_lshl_add_u64 v[228:229], s[38:39], 0, v[132:133]
	s_mov_b32 m0, s40
	v_lshl_add_u64 v[230:231], s[12:13], 0, v[134:135]
	global_load_lds_dwordx4 v[228:229], off
	v_lshl_add_u64 v[228:229], s[38:39], 0, v[136:137]
	s_add_i32 m0, s40, 0x2000
	s_nop 0
	global_load_lds_dwordx4 v[228:229], off
	v_lshl_add_u64 v[228:229], s[12:13], 0, v[130:131]
	s_mov_b32 m0, s17
	s_nop 0
	global_load_lds_dwordx4 v[228:229], off
	s_mov_b32 m0, s24
	s_nop 0
	global_load_lds_dwordx4 v[230:231], off
	s_waitcnt vmcnt(8)
	s_waitcnt lgkmcnt(0)
	v_mfma_f32_16x16x32_bf16 v[62:65], v[148:151], v[192:195], v[62:65]
	v_mfma_f32_16x16x32_bf16 v[58:61], v[156:159], v[192:195], v[58:61]
	v_mfma_f32_16x16x32_bf16 v[46:49], v[148:151], v[202:205], v[46:49]
	v_mfma_f32_16x16x32_bf16 v[42:45], v[156:159], v[202:205], v[42:45]
	v_mfma_f32_16x16x32_bf16 v[30:33], v[148:151], v[210:213], v[30:33]
	v_mfma_f32_16x16x32_bf16 v[26:29], v[156:159], v[210:213], v[26:29]
	v_mfma_f32_16x16x32_bf16 v[14:17], v[148:151], v[218:221], v[14:17]
	v_mfma_f32_16x16x32_bf16 v[10:13], v[156:159], v[218:221], v[10:13]
	s_barrier
; #define PG8_STAGE(bufoff, gbase, voff) do { _Pragma("unroll") for (int _i = 0; _i < 2; ++_i) \
;         __builtin_amdgcn_global_load_lds((const unsigned*)((const char*)(gbase) + (voff)[_i]), (PG8_LAS unsigned*)(lds + (bufoff) + ldsw + _i * 8192), 16, 0, 0); } while (0)
; #define PG8_LDA(dst, b, h) do { _Pragma("unroll") for (int m = 0; m < 4; ++m) _Pragma("unroll") for (int k = 0; k < 2; ++k) dst[m][k] = *(const PG8_LAS bf16x8*)(lds + PG8_SA(b, h) + aoff + m * 2048 + k * 1024); } while (0)
; #define PG8_LDB(dst, b, h) do { _Pragma("unroll") for (int n = 0; n < 2; ++n) _Pragma("unroll") for (int k = 0; k < 2; ++k) dst[n][k] = *(const PG8_LAS bf16x8*)(lds + PG8_SB(b, h) + boff + n * 2048 + k * 1024); } while (0)
; #define PG8_MMA(ai, bj, At, Bt) do { __builtin_amdgcn_s_setprio(1); _Pragma("unroll") for (int m = 0; m < 4; ++m) _Pragma("unroll") for (int n = 0; n < 2; ++n) _Pragma("unroll") for (int k = 0; k < 2; ++k) \
;         acc[ai][bj][m][n] = __builtin_amdgcn_mfma_f32_16x16x32_bf16(Bt[n][k], At[m][k], acc[ai][bj][m][n], 0, 0, 0); __builtin_amdgcn_s_setprio(0); } while (0)
; #define PG8_WAIT_V(n) asm volatile("s_waitcnt vmcnt(" #n ")" ::: "memory")
; #define PG8_WAIT_L(n) asm volatile("s_waitcnt lgkmcnt(" #n ")" ::: "memory")
; #define PG8_BAR __builtin_amdgcn_s_barrier()
; #define PG8_SCHED __builtin_amdgcn_sched_barrier(0)
; template <class Epi, class Sched, bool ALIGN_EPI = false, bool SP2 = false>
; __device__ __forceinline__ void gemm_phase(PG8_LAS unsigned char* lds, const Gemm g, const Sched& S, const Epi& E) {
;     ...
;             PG8_WAIT_V(8); PG8_WAIT_L(0); PG8_BAR; PG8_MMA(1, 0, At, B0); PG8_MMA(1, 1, At, B1); PG8_BAR; PG8_SCHED;
;             PG8_LDB(B0, 1, 0); PG8_LDB(B1, 1, 1); PG8_SCHED; PG8_LDA(At, 1, 0); PG8_STAGE(PG8_SA(0, 1), a2 + hstep, voffA);
;             PG8_WAIT_V(8); PG8_WAIT_L(0); PG8_BAR; PG8_MMA(0, 0, At, B0); PG8_MMA(0, 1, At, B1); PG8_BAR; PG8_SCHED;
	s_setprio 1
	s_waitcnt lgkmcnt(0)
	v_mfma_f32_16x16x32_bf16 v[62:65], v[152:155], v[198:201], v[62:65]
	v_mfma_f32_16x16x32_bf16 v[58:61], v[172:175], v[198:201], v[58:61]
	v_mfma_f32_16x16x32_bf16 v[46:49], v[152:155], v[206:209], v[46:49]
	v_mfma_f32_16x16x32_bf16 v[42:45], v[172:175], v[206:209], v[42:45]
	v_mfma_f32_16x16x32_bf16 v[30:33], v[152:155], v[214:217], v[30:33]
	v_mfma_f32_16x16x32_bf16 v[26:29], v[172:175], v[214:217], v[26:29]
	v_mfma_f32_16x16x32_bf16 v[14:17], v[152:155], v[222:225], v[14:17]
	v_mfma_f32_16x16x32_bf16 v[10:13], v[172:175], v[222:225], v[10:13]
	s_setprio 0
	s_setprio 1
	v_mfma_f32_16x16x32_bf16 v[54:57], v[176:179], v[192:195], v[54:57]
	v_mfma_f32_16x16x32_bf16 v[50:53], v[184:187], v[192:195], v[50:53]
	v_mfma_f32_16x16x32_bf16 v[38:41], v[176:179], v[202:205], v[38:41]
	v_mfma_f32_16x16x32_bf16 v[34:37], v[184:187], v[202:205], v[34:37]
	v_mfma_f32_16x16x32_bf16 v[22:25], v[176:179], v[210:213], v[22:25]
	v_mfma_f32_16x16x32_bf16 v[18:21], v[184:187], v[210:213], v[18:21]
	v_mfma_f32_16x16x32_bf16 v[6:9], v[176:179], v[218:221], v[6:9]
	v_mfma_f32_16x16x32_bf16 v[2:5], v[184:187], v[218:221], v[2:5]
	v_mfma_f32_16x16x32_bf16 v[54:57], v[180:183], v[198:201], v[54:57]
	v_mfma_f32_16x16x32_bf16 v[50:53], v[188:191], v[198:201], v[50:53]
	v_mfma_f32_16x16x32_bf16 v[38:41], v[180:183], v[206:209], v[38:41]
	v_mfma_f32_16x16x32_bf16 v[34:37], v[188:191], v[206:209], v[34:37]
	v_mfma_f32_16x16x32_bf16 v[22:25], v[180:183], v[214:217], v[22:25]
	v_mfma_f32_16x16x32_bf16 v[18:21], v[188:191], v[214:217], v[18:21]
	v_mfma_f32_16x16x32_bf16 v[6:9], v[180:183], v[222:225], v[6:9]
	v_mfma_f32_16x16x32_bf16 v[2:5], v[188:191], v[222:225], v[2:5]
	s_setprio 0
	s_barrier
	s_add_i32 s38, 0, 0x18000
	v_add_u32_e32 v138, s38, v162
	s_add_i32 s39, 0, 0x1c000
	ds_read_b128 v[148:151], v138
	ds_read_b128 v[152:155], v138 offset:1024
	ds_read_b128 v[156:159], v138 offset:2048
	ds_read_b128 v[172:175], v138 offset:3072
	v_add_u32_e32 v138, s39, v162
	ds_read_b128 v[176:179], v138
	ds_read_b128 v[180:183], v138 offset:1024
	ds_read_b128 v[184:187], v138 offset:2048
	ds_read_b128 v[188:191], v138 offset:3072
	s_add_u32 s12, s12, 0x40000
	s_addc_u32 s13, s13, 0
	s_mov_b32 m0, s25
	v_lshl_add_u64 v[232:233], s[12:13], 0, v[130:131]
	ds_read_b128 v[192:195], v166 offset:32768
	ds_read_b128 v[198:201], v166 offset:33792
	ds_read_b128 v[202:205], v166 offset:34816
	ds_read_b128 v[206:209], v166 offset:35840
	ds_read_b128 v[210:213], v166 offset:36864
	ds_read_b128 v[214:217], v166 offset:37888
	ds_read_b128 v[218:221], v166 offset:38912
	ds_read_b128 v[222:225], v166 offset:39936
	global_load_lds_dwordx4 v[232:233], off
	v_lshl_add_u64 v[232:233], s[12:13], 0, v[134:135]
	s_mov_b32 m0, s26
	s_nop 0
	global_load_lds_dwordx4 v[232:233], off
	s_waitcnt vmcnt(8)
	s_waitcnt lgkmcnt(0)
	v_mfma_f32_16x16x32_bf16 v[126:129], v[148:151], v[192:195], v[126:129]
	v_mfma_f32_16x16x32_bf16 v[122:125], v[156:159], v[192:195], v[122:125]
	v_mfma_f32_16x16x32_bf16 v[110:113], v[148:151], v[202:205], v[110:113]
	v_mfma_f32_16x16x32_bf16 v[106:109], v[156:159], v[202:205], v[106:109]
	v_mfma_f32_16x16x32_bf16 v[94:97], v[148:151], v[210:213], v[94:97]
	v_mfma_f32_16x16x32_bf16 v[90:93], v[156:159], v[210:213], v[90:93]
	v_mfma_f32_16x16x32_bf16 v[78:81], v[148:151], v[218:221], v[78:81]
	v_mfma_f32_16x16x32_bf16 v[74:77], v[156:159], v[218:221], v[74:77]
	s_barrier
	s_setprio 1
	s_waitcnt lgkmcnt(0)
	v_mfma_f32_16x16x32_bf16 v[126:129], v[152:155], v[198:201], v[126:129]
	v_mfma_f32_16x16x32_bf16 v[122:125], v[172:175], v[198:201], v[122:125]
	v_mfma_f32_16x16x32_bf16 v[110:113], v[152:155], v[206:209], v[110:113]
	v_mfma_f32_16x16x32_bf16 v[106:109], v[172:175], v[206:209], v[106:109]
	v_mfma_f32_16x16x32_bf16 v[94:97], v[152:155], v[214:217], v[94:97]
	v_mfma_f32_16x16x32_bf16 v[90:93], v[172:175], v[214:217], v[90:93]
	v_mfma_f32_16x16x32_bf16 v[78:81], v[152:155], v[222:225], v[78:81]
	v_mfma_f32_16x16x32_bf16 v[74:77], v[172:175], v[222:225], v[74:77]
	s_setprio 0
	s_setprio 1
	v_mfma_f32_16x16x32_bf16 v[118:121], v[176:179], v[192:195], v[118:121]
	v_mfma_f32_16x16x32_bf16 v[114:117], v[184:187], v[192:195], v[114:117]
	v_mfma_f32_16x16x32_bf16 v[102:105], v[176:179], v[202:205], v[102:105]
	v_mfma_f32_16x16x32_bf16 v[98:101], v[184:187], v[202:205], v[98:101]
	v_mfma_f32_16x16x32_bf16 v[86:89], v[176:179], v[210:213], v[86:89]
	v_mfma_f32_16x16x32_bf16 v[82:85], v[184:187], v[210:213], v[82:85]
	v_mfma_f32_16x16x32_bf16 v[70:73], v[176:179], v[218:221], v[70:73]
	v_mfma_f32_16x16x32_bf16 v[66:69], v[184:187], v[218:221], v[66:69]
	v_mfma_f32_16x16x32_bf16 v[118:121], v[180:183], v[198:201], v[118:121]
	v_mfma_f32_16x16x32_bf16 v[114:117], v[188:191], v[198:201], v[114:117]
	v_mfma_f32_16x16x32_bf16 v[102:105], v[180:183], v[206:209], v[102:105]
	v_mfma_f32_16x16x32_bf16 v[98:101], v[188:191], v[206:209], v[98:101]
	v_mfma_f32_16x16x32_bf16 v[86:89], v[180:183], v[214:217], v[86:89]
	v_mfma_f32_16x16x32_bf16 v[82:85], v[188:191], v[214:217], v[82:85]
	v_mfma_f32_16x16x32_bf16 v[70:73], v[180:183], v[222:225], v[70:73]
	v_mfma_f32_16x16x32_bf16 v[66:69], v[188:191], v[222:225], v[66:69]
	s_setprio 0
	s_barrier
; #define PG8_STAGE(bufoff, gbase, voff) do { _Pragma("unroll") for (int _i = 0; _i < 2; ++_i) \
;         __builtin_amdgcn_global_load_lds((const unsigned*)((const char*)(gbase) + (voff)[_i]), (PG8_LAS unsigned*)(lds + (bufoff) + ldsw + _i * 8192), 16, 0, 0); } while (0)
; #define PG8_LDA(dst, b, h) do { _Pragma("unroll") for (int m = 0; m < 4; ++m) _Pragma("unroll") for (int k = 0; k < 2; ++k) dst[m][k] = *(const PG8_LAS bf16x8*)(lds + PG8_SA(b, h) + aoff + m * 2048 + k * 1024); } while (0)
; #define PG8_MMA(ai, bj, At, Bt) do { __builtin_amdgcn_s_setprio(1); _Pragma("unroll") for (int m = 0; m < 4; ++m) _Pragma("unroll") for (int n = 0; n < 2; ++n) _Pragma("unroll") for (int k = 0; k < 2; ++k) \
;         acc[ai][bj][m][n] = __builtin_amdgcn_mfma_f32_16x16x32_bf16(Bt[n][k], At[m][k], acc[ai][bj][m][n], 0, 0, 0); __builtin_amdgcn_s_setprio(0); } while (0)
; #define PG8_WAIT_V(n) asm volatile("s_waitcnt vmcnt(" #n ")" ::: "memory")
; #define PG8_WAIT_L(n) asm volatile("s_waitcnt lgkmcnt(" #n ")" ::: "memory")
; #define PG8_BAR __builtin_amdgcn_s_barrier()
; #define PG8_SCHED __builtin_amdgcn_sched_barrier(0)
; template <class Epi, class Sched, bool ALIGN_EPI = false, bool SP2 = false>
; __device__ __forceinline__ void gemm_phase(PG8_LAS unsigned char* lds, const Gemm g, const Sched& S, const Epi& E) {
;     ...
;             PG8_LDA(At, 1, 1); PG8_STAGE(PG8_SB(1, 0), b3, voffB); PG8_STAGE(PG8_SB(1, 1), b3 + hstep, voffB); PG8_STAGE(PG8_SA(1, 0), a3, voffA);
;             PG8_WAIT_V(8); PG8_WAIT_L(0); PG8_BAR; PG8_MMA(1, 0, At, B0); PG8_MMA(1, 1, At, B1); PG8_BAR; PG8_SCHED;
;     ...
;         if constexpr (ALIGN_EPI) { if (wr == 0) PG8_BAR; }
	s_add_i32 s12, s38, s16
	v_lshl_add_u64 v[160:161], v[160:161], 0, s[20:21]
	s_mov_b32 m0, s12
	ds_read_b128 v[192:195], v166 offset:49152
	ds_read_b128 v[198:201], v166 offset:50176
	ds_read_b128 v[202:205], v166 offset:51200
	ds_read_b128 v[206:209], v166 offset:52224
	ds_read_b128 v[210:213], v166 offset:53248
	ds_read_b128 v[214:217], v166 offset:54272
	ds_read_b128 v[218:221], v166 offset:55296
	ds_read_b128 v[222:225], v166 offset:56320
	global_load_lds_dwordx4 v[160:161], off
	s_add_i32 m0, s12, 0x2000
	s_add_u32 s2, s2, 0x40080
	v_lshl_add_u64 v[160:161], v[226:227], 0, s[20:21]
	s_addc_u32 s3, s3, 0
	s_add_i32 s12, s39, s16
	global_load_lds_dwordx4 v[160:161], off
	v_lshl_add_u64 v[160:161], s[2:3], 0, v[132:133]
	s_mov_b32 m0, s12
	s_nop 0
	global_load_lds_dwordx4 v[160:161], off
	v_lshl_add_u64 v[160:161], s[2:3], 0, v[136:137]
	s_add_i32 m0, s12, 0x2000
	s_nop 0
	global_load_lds_dwordx4 v[160:161], off
	v_lshl_add_u64 v[160:161], v[228:229], 0, s[20:21]
	s_mov_b32 m0, s34
	s_nop 0
	global_load_lds_dwordx4 v[160:161], off
	v_lshl_add_u64 v[160:161], v[230:231], 0, s[20:21]
	s_mov_b32 m0, s35
	s_nop 0
	global_load_lds_dwordx4 v[160:161], off
	s_waitcnt vmcnt(8)
	s_waitcnt lgkmcnt(0)
	v_mfma_f32_16x16x32_bf16 v[62:65], v[148:151], v[192:195], v[62:65]
	v_mfma_f32_16x16x32_bf16 v[58:61], v[156:159], v[192:195], v[58:61]
	v_mfma_f32_16x16x32_bf16 v[46:49], v[148:151], v[202:205], v[46:49]
	v_mfma_f32_16x16x32_bf16 v[42:45], v[156:159], v[202:205], v[42:45]
	v_mfma_f32_16x16x32_bf16 v[30:33], v[148:151], v[210:213], v[30:33]
	v_mfma_f32_16x16x32_bf16 v[26:29], v[156:159], v[210:213], v[26:29]
	v_mfma_f32_16x16x32_bf16 v[14:17], v[148:151], v[218:221], v[14:17]
	v_mfma_f32_16x16x32_bf16 v[10:13], v[156:159], v[218:221], v[10:13]
	s_barrier
	s_setprio 1
	s_waitcnt lgkmcnt(0)
	v_mfma_f32_16x16x32_bf16 v[62:65], v[152:155], v[198:201], v[62:65]
	v_mfma_f32_16x16x32_bf16 v[58:61], v[172:175], v[198:201], v[58:61]
	v_mfma_f32_16x16x32_bf16 v[46:49], v[152:155], v[206:209], v[46:49]
	v_mfma_f32_16x16x32_bf16 v[42:45], v[172:175], v[206:209], v[42:45]
	v_mfma_f32_16x16x32_bf16 v[30:33], v[152:155], v[214:217], v[30:33]
	v_mfma_f32_16x16x32_bf16 v[26:29], v[172:175], v[214:217], v[26:29]
	v_mfma_f32_16x16x32_bf16 v[14:17], v[152:155], v[222:225], v[14:17]
	v_mfma_f32_16x16x32_bf16 v[10:13], v[172:175], v[222:225], v[10:13]
	s_setprio 0
	s_setprio 1
	v_mfma_f32_16x16x32_bf16 v[54:57], v[176:179], v[192:195], v[54:57]
	v_mfma_f32_16x16x32_bf16 v[50:53], v[184:187], v[192:195], v[50:53]
	v_mfma_f32_16x16x32_bf16 v[38:41], v[176:179], v[202:205], v[38:41]
	v_mfma_f32_16x16x32_bf16 v[34:37], v[184:187], v[202:205], v[34:37]
	v_mfma_f32_16x16x32_bf16 v[22:25], v[176:179], v[210:213], v[22:25]
	v_mfma_f32_16x16x32_bf16 v[18:21], v[184:187], v[210:213], v[18:21]
	v_mfma_f32_16x16x32_bf16 v[6:9], v[176:179], v[218:221], v[6:9]
	v_mfma_f32_16x16x32_bf16 v[2:5], v[184:187], v[218:221], v[2:5]
	v_mfma_f32_16x16x32_bf16 v[54:57], v[180:183], v[198:201], v[54:57]
	v_mfma_f32_16x16x32_bf16 v[50:53], v[188:191], v[198:201], v[50:53]
	v_mfma_f32_16x16x32_bf16 v[38:41], v[180:183], v[206:209], v[38:41]
	v_mfma_f32_16x16x32_bf16 v[34:37], v[188:191], v[206:209], v[34:37]
	v_mfma_f32_16x16x32_bf16 v[22:25], v[180:183], v[214:217], v[22:25]
	v_mfma_f32_16x16x32_bf16 v[18:21], v[188:191], v[214:217], v[18:21]
	v_mfma_f32_16x16x32_bf16 v[6:9], v[180:183], v[222:225], v[6:9]
	v_mfma_f32_16x16x32_bf16 v[2:5], v[188:191], v[222:225], v[2:5]
	s_setprio 0
	s_barrier
	s_add_i32 s37, s37, 2
	s_add_u32 s10, s10, 0x100
	s_addc_u32 s11, s11, 0
	s_add_u32 s29, s29, 0x100
	s_addc_u32 s36, s36, 0
	s_cmp_gt_u32 s37, 13
	s_cbranch_scc0 .LBB0_334
	s_and_b64 vcc, exec, s[22:23]
	s_cbranch_vccz .LBB0_337
	s_barrier

; #define PG8_STAGE(bufoff, gbase, voff) do { _Pragma("unroll") for (int _i = 0; _i < 2; ++_i) \
;         __builtin_amdgcn_global_load_lds((const unsigned*)((const char*)(gbase) + (voff)[_i]), (PG8_LAS unsigned*)(lds + (bufoff) + ldsw + _i * 8192), 16, 0, 0); } while (0)
; #define PG8_LDA(dst, b, h) do { _Pragma("unroll") for (int m = 0; m < 4; ++m) _Pragma("unroll") for (int k = 0; k < 2; ++k) dst[m][k] = *(const PG8_LAS bf16x8*)(lds + PG8_SA(b, h) + aoff + m * 2048 + k * 1024); } while (0)
; #define PG8_LDB(dst, b, h) do { _Pragma("unroll") for (int n = 0; n < 2; ++n) _Pragma("unroll") for (int k = 0; k < 2; ++k) dst[n][k] = *(const PG8_LAS bf16x8*)(lds + PG8_SB(b, h) + boff + n * 2048 + k * 1024); } while (0)
; #define PG8_MMA(ai, bj, At, Bt) do { __builtin_amdgcn_s_setprio(1); _Pragma("unroll") for (int m = 0; m < 4; ++m) _Pragma("unroll") for (int n = 0; n < 2; ++n) _Pragma("unroll") for (int k = 0; k < 2; ++k) \
;         acc[ai][bj][m][n] = __builtin_amdgcn_mfma_f32_16x16x32_bf16(Bt[n][k], At[m][k], acc[ai][bj][m][n], 0, 0, 0); __builtin_amdgcn_s_setprio(0); } while (0)
; #define PG8_WAIT_V(n) asm volatile("s_waitcnt vmcnt(" #n ")" ::: "memory")
; #define PG8_WAIT_L(n) asm volatile("s_waitcnt lgkmcnt(" #n ")" ::: "memory")
; template <class Epi, class Sched, bool ALIGN_EPI = false, bool SP2 = false>
; __device__ __forceinline__ void gemm_phase(PG8_LAS unsigned char* lds, const Gemm g, const Sched& S, const Epi& E) {
;     ...
;             const bool last = (t == nt - 2);
;             const char* a1 = cA + (size_t)(t + 1) * kstep;
;             const char* a2 = last ? nA : cA + (size_t)(t + 2) * kstep; const char* b2 = last ? nB : cB + (size_t)(t + 2) * kstep;
;             const char* a3 = a2 + kstep; const char* b3 = b2 + kstep;
;             if (last && has_next) S.a_ready(nxt);
;             if constexpr (SP2) {
;             PG8_LDB(B0, 0, 0); PG8_LDB(B1, 0, 1); PG8_SCHED; PG8_LDA(At, 0, 0); PG8_STAGE(PG8_SA(1, 1), a1 + hstep, voffA);
;             PG8_WAIT_V(8); PG8_WAIT_L(0); PG8_BAR; PG8_MMA(0, 0, At, B0); PG8_MMA(0, 1, At, B1); PG8_BAR; PG8_SCHED;
;             PG8_LDA(At, 0, 1); PG8_STAGE(PG8_SB(0, 0), b2, voffB); PG8_STAGE(PG8_SB(0, 1), b2 + hstep, voffB); PG8_STAGE(PG8_SA(0, 0), a2, voffA);
;             PG8_WAIT_V(8); PG8_WAIT_L(0); PG8_BAR; PG8_MMA(1, 0, At, B0); PG8_MMA(1, 1, At, B1); PG8_BAR; PG8_SCHED;
.LBB0_1488:
	v_add_u32_e32 v162, s43, v152
	ds_read_b128 v[154:157], v162
	ds_read_b128 v[158:161], v162 offset:1024
	ds_read_b128 v[166:169], v162 offset:2048
	ds_read_b128 v[170:173], v162 offset:3072
	v_add_u32_e32 v162, s44, v152
	s_add_u32 s2, s0, s40
	ds_read_b128 v[174:177], v162
	ds_read_b128 v[178:181], v162 offset:1024
	ds_read_b128 v[182:185], v162 offset:2048
	ds_read_b128 v[186:189], v162 offset:3072
	s_addc_u32 s3, s1, s41
	s_add_u32 s2, s2, 0x100
	s_addc_u32 s3, s3, 0
	s_add_u32 s51, s46, s40
	s_addc_u32 s52, s47, s41
	s_cmpk_eq_i32 s40, 0x700
	s_cselect_b32 s15, s29, s3
	s_cselect_b32 s14, s48, s2
	s_cselect_b32 s3, s25, s52
	s_cselect_b32 s2, s49, s51
	v_lshl_add_u64 v[162:163], v[146:147], 0, s[40:41]
	s_add_i32 m0, s26, 0xc000
	ds_read_b128 v[190:193], v153
	ds_read_b128 v[194:197], v153 offset:1024
	ds_read_b128 v[198:201], v153 offset:2048
	ds_read_b128 v[202:205], v153 offset:3072
	ds_read_b128 v[206:209], v153 offset:4096
	ds_read_b128 v[210:213], v153 offset:5120
	ds_read_b128 v[214:217], v153 offset:6144
	ds_read_b128 v[218:221], v153 offset:7168
	global_load_lds_dwordx4 v[162:163], off
	v_lshl_add_u64 v[162:163], v[148:149], 0, s[40:41]
	s_add_i32 m0, s26, 0xe000
	s_nop 0
	global_load_lds_dwordx4 v[162:163], off
	s_waitcnt vmcnt(8)
	s_waitcnt lgkmcnt(0)
	v_mfma_f32_16x16x32_bf16 v[94:97], v[154:157], v[190:193], v[94:97]
	v_mfma_f32_16x16x32_bf16 v[102:105], v[166:169], v[190:193], v[102:105]
	v_mfma_f32_16x16x32_bf16 v[106:109], v[154:157], v[198:201], v[106:109]
	v_mfma_f32_16x16x32_bf16 v[110:113], v[166:169], v[198:201], v[110:113]
	v_mfma_f32_16x16x32_bf16 v[114:117], v[154:157], v[206:209], v[114:117]
	v_mfma_f32_16x16x32_bf16 v[122:125], v[166:169], v[206:209], v[122:125]
	v_mfma_f32_16x16x32_bf16 v[126:129], v[154:157], v[214:217], v[126:129]
	v_mfma_f32_16x16x32_bf16 v[118:121], v[166:169], v[214:217], v[118:121]
	s_barrier
	s_setprio 1
	s_waitcnt lgkmcnt(0)
	v_mfma_f32_16x16x32_bf16 v[94:97], v[158:161], v[194:197], v[94:97]
	v_mfma_f32_16x16x32_bf16 v[102:105], v[170:173], v[194:197], v[102:105]
	v_mfma_f32_16x16x32_bf16 v[106:109], v[158:161], v[202:205], v[106:109]
	v_mfma_f32_16x16x32_bf16 v[110:113], v[170:173], v[202:205], v[110:113]
	v_mfma_f32_16x16x32_bf16 v[114:117], v[158:161], v[210:213], v[114:117]
	v_mfma_f32_16x16x32_bf16 v[122:125], v[170:173], v[210:213], v[122:125]
	v_mfma_f32_16x16x32_bf16 v[126:129], v[158:161], v[218:221], v[126:129]
	v_mfma_f32_16x16x32_bf16 v[118:121], v[170:173], v[218:221], v[118:121]
	s_setprio 0
	s_setprio 1
	v_mfma_f32_16x16x32_bf16 v[90:93], v[174:177], v[190:193], v[90:93]
	v_mfma_f32_16x16x32_bf16 v[74:77], v[182:185], v[190:193], v[74:77]
	v_mfma_f32_16x16x32_bf16 v[78:81], v[174:177], v[198:201], v[78:81]
	v_mfma_f32_16x16x32_bf16 v[66:69], v[182:185], v[198:201], v[66:69]
	v_mfma_f32_16x16x32_bf16 v[98:101], v[174:177], v[206:209], v[98:101]
	v_mfma_f32_16x16x32_bf16 v[86:89], v[182:185], v[206:209], v[86:89]
	v_mfma_f32_16x16x32_bf16 v[82:85], v[174:177], v[214:217], v[82:85]
	v_mfma_f32_16x16x32_bf16 v[70:73], v[182:185], v[214:217], v[70:73]
	v_mfma_f32_16x16x32_bf16 v[90:93], v[178:181], v[194:197], v[90:93]
	v_mfma_f32_16x16x32_bf16 v[74:77], v[186:189], v[194:197], v[74:77]
	v_mfma_f32_16x16x32_bf16 v[78:81], v[178:181], v[202:205], v[78:81]
	v_mfma_f32_16x16x32_bf16 v[66:69], v[186:189], v[202:205], v[66:69]
	v_mfma_f32_16x16x32_bf16 v[98:101], v[178:181], v[210:213], v[98:101]
	v_mfma_f32_16x16x32_bf16 v[86:89], v[186:189], v[210:213], v[86:89]
	v_mfma_f32_16x16x32_bf16 v[82:85], v[178:181], v[218:221], v[82:85]
	v_mfma_f32_16x16x32_bf16 v[70:73], v[186:189], v[218:221], v[70:73]
	s_setprio 0
	s_barrier
	s_add_i32 s51, s43, s21
	v_lshl_add_u64 v[162:163], s[2:3], 0, v[132:133]
	s_mov_b32 m0, s51
	ds_read_b128 v[190:193], v153 offset:16384
	ds_read_b128 v[194:197], v153 offset:17408
	ds_read_b128 v[198:201], v153 offset:18432
	ds_read_b128 v[202:205], v153 offset:19456
	ds_read_b128 v[206:209], v153 offset:20480
	ds_read_b128 v[210:213], v153 offset:21504
	ds_read_b128 v[214:217], v153 offset:22528
	ds_read_b128 v[218:221], v153 offset:23552
	global_load_lds_dwordx4 v[162:163], off
	s_add_i32 m0, s51, 0x2000
	s_add_u32 s52, s2, 0x40000
	v_lshl_add_u64 v[222:223], s[2:3], 0, v[136:137]
	s_addc_u32 s53, s3, 0
	s_add_i32 s51, s44, s21
	global_load_lds_dwordx4 v[222:223], off
	v_lshl_add_u64 v[224:225], s[52:53], 0, v[132:133]
	s_mov_b32 m0, s51
	v_lshl_add_u64 v[226:227], s[14:15], 0, v[134:135]
	global_load_lds_dwordx4 v[224:225], off
	v_lshl_add_u64 v[224:225], s[52:53], 0, v[136:137]
	s_add_i32 m0, s51, 0x2000
	s_nop 0
	global_load_lds_dwordx4 v[224:225], off
	v_lshl_add_u64 v[224:225], s[14:15], 0, v[130:131]
	s_mov_b32 m0, s26
	s_nop 0
	global_load_lds_dwordx4 v[224:225], off
	s_mov_b32 m0, s27
	s_nop 0
	global_load_lds_dwordx4 v[226:227], off
	s_waitcnt vmcnt(8)
	s_waitcnt lgkmcnt(0)
	v_mfma_f32_16x16x32_bf16 v[62:65], v[154:157], v[190:193], v[62:65]
	v_mfma_f32_16x16x32_bf16 v[58:61], v[166:169], v[190:193], v[58:61]
	v_mfma_f32_16x16x32_bf16 v[46:49], v[154:157], v[198:201], v[46:49]
	v_mfma_f32_16x16x32_bf16 v[42:45], v[166:169], v[198:201], v[42:45]
	v_mfma_f32_16x16x32_bf16 v[30:33], v[154:157], v[206:209], v[30:33]
	v_mfma_f32_16x16x32_bf16 v[26:29], v[166:169], v[206:209], v[26:29]
	v_mfma_f32_16x16x32_bf16 v[14:17], v[154:157], v[214:217], v[14:17]
	v_mfma_f32_16x16x32_bf16 v[10:13], v[166:169], v[214:217], v[10:13]
	s_barrier
; #define PG8_STAGE(bufoff, gbase, voff) do { _Pragma("unroll") for (int _i = 0; _i < 2; ++_i) \
;         __builtin_amdgcn_global_load_lds((const unsigned*)((const char*)(gbase) + (voff)[_i]), (PG8_LAS unsigned*)(lds + (bufoff) + ldsw + _i * 8192), 16, 0, 0); } while (0)
; #define PG8_LDA(dst, b, h) do { _Pragma("unroll") for (int m = 0; m < 4; ++m) _Pragma("unroll") for (int k = 0; k < 2; ++k) dst[m][k] = *(const PG8_LAS bf16x8*)(lds + PG8_SA(b, h) + aoff + m * 2048 + k * 1024); } while (0)
; #define PG8_LDB(dst, b, h) do { _Pragma("unroll") for (int n = 0; n < 2; ++n) _Pragma("unroll") for (int k = 0; k < 2; ++k) dst[n][k] = *(const PG8_LAS bf16x8*)(lds + PG8_SB(b, h) + boff + n * 2048 + k * 1024); } while (0)
; #define PG8_MMA(ai, bj, At, Bt) do { __builtin_amdgcn_s_setprio(1); _Pragma("unroll") for (int m = 0; m < 4; ++m) _Pragma("unroll") for (int n = 0; n < 2; ++n) _Pragma("unroll") for (int k = 0; k < 2; ++k) \
;         acc[ai][bj][m][n] = __builtin_amdgcn_mfma_f32_16x16x32_bf16(Bt[n][k], At[m][k], acc[ai][bj][m][n], 0, 0, 0); __builtin_amdgcn_s_setprio(0); } while (0)
; #define PG8_WAIT_V(n) asm volatile("s_waitcnt vmcnt(" #n ")" ::: "memory")
; #define PG8_WAIT_L(n) asm volatile("s_waitcnt lgkmcnt(" #n ")" ::: "memory")
; #define PG8_BAR __builtin_amdgcn_s_barrier()
; #define PG8_SCHED __builtin_amdgcn_sched_barrier(0)
; template <class Epi, class Sched, bool ALIGN_EPI = false, bool SP2 = false>
; __device__ __forceinline__ void gemm_phase(PG8_LAS unsigned char* lds, const Gemm g, const Sched& S, const Epi& E) {
;     ...
;             PG8_WAIT_V(8); PG8_WAIT_L(0); PG8_BAR; PG8_MMA(1, 0, At, B0); PG8_MMA(1, 1, At, B1); PG8_BAR; PG8_SCHED;
;             PG8_LDB(B0, 1, 0); PG8_LDB(B1, 1, 1); PG8_SCHED; PG8_LDA(At, 1, 0); PG8_STAGE(PG8_SA(0, 1), a2 + hstep, voffA);
;             PG8_WAIT_V(8); PG8_WAIT_L(0); PG8_BAR; PG8_MMA(0, 0, At, B0); PG8_MMA(0, 1, At, B1); PG8_BAR; PG8_SCHED;
	s_setprio 1
	s_waitcnt lgkmcnt(0)
	v_mfma_f32_16x16x32_bf16 v[62:65], v[158:161], v[194:197], v[62:65]
	v_mfma_f32_16x16x32_bf16 v[58:61], v[170:173], v[194:197], v[58:61]
	v_mfma_f32_16x16x32_bf16 v[46:49], v[158:161], v[202:205], v[46:49]
	v_mfma_f32_16x16x32_bf16 v[42:45], v[170:173], v[202:205], v[42:45]
	v_mfma_f32_16x16x32_bf16 v[30:33], v[158:161], v[210:213], v[30:33]
	v_mfma_f32_16x16x32_bf16 v[26:29], v[170:173], v[210:213], v[26:29]
	v_mfma_f32_16x16x32_bf16 v[14:17], v[158:161], v[218:221], v[14:17]
	v_mfma_f32_16x16x32_bf16 v[10:13], v[170:173], v[218:221], v[10:13]
	s_setprio 0
	s_setprio 1
	v_mfma_f32_16x16x32_bf16 v[54:57], v[174:177], v[190:193], v[54:57]
	v_mfma_f32_16x16x32_bf16 v[50:53], v[182:185], v[190:193], v[50:53]
	v_mfma_f32_16x16x32_bf16 v[38:41], v[174:177], v[198:201], v[38:41]
	v_mfma_f32_16x16x32_bf16 v[34:37], v[182:185], v[198:201], v[34:37]
	v_mfma_f32_16x16x32_bf16 v[22:25], v[174:177], v[206:209], v[22:25]
	v_mfma_f32_16x16x32_bf16 v[18:21], v[182:185], v[206:209], v[18:21]
	v_mfma_f32_16x16x32_bf16 v[6:9], v[174:177], v[214:217], v[6:9]
	v_mfma_f32_16x16x32_bf16 v[2:5], v[182:185], v[214:217], v[2:5]
	v_mfma_f32_16x16x32_bf16 v[54:57], v[178:181], v[194:197], v[54:57]
	v_mfma_f32_16x16x32_bf16 v[50:53], v[186:189], v[194:197], v[50:53]
	v_mfma_f32_16x16x32_bf16 v[38:41], v[178:181], v[202:205], v[38:41]
	v_mfma_f32_16x16x32_bf16 v[34:37], v[186:189], v[202:205], v[34:37]
	v_mfma_f32_16x16x32_bf16 v[22:25], v[178:181], v[210:213], v[22:25]
	v_mfma_f32_16x16x32_bf16 v[18:21], v[186:189], v[210:213], v[18:21]
	v_mfma_f32_16x16x32_bf16 v[6:9], v[178:181], v[218:221], v[6:9]
	v_mfma_f32_16x16x32_bf16 v[2:5], v[186:189], v[218:221], v[2:5]
	s_setprio 0
	s_barrier
	s_add_i32 s51, 0, 0x18000
	v_add_u32_e32 v165, s51, v152
	s_add_i32 s52, 0, 0x1c000
	ds_read_b128 v[154:157], v165
	ds_read_b128 v[158:161], v165 offset:1024
	ds_read_b128 v[166:169], v165 offset:2048
	ds_read_b128 v[170:173], v165 offset:3072
	v_add_u32_e32 v165, s52, v152
	ds_read_b128 v[174:177], v165
	ds_read_b128 v[178:181], v165 offset:1024
	ds_read_b128 v[182:185], v165 offset:2048
	ds_read_b128 v[186:189], v165 offset:3072
	s_add_u32 s14, s14, 0x40000
	s_addc_u32 s15, s15, 0
	s_mov_b32 m0, s33
	v_lshl_add_u64 v[228:229], s[14:15], 0, v[130:131]
	ds_read_b128 v[190:193], v153 offset:32768
	ds_read_b128 v[194:197], v153 offset:33792
	ds_read_b128 v[198:201], v153 offset:34816
	ds_read_b128 v[202:205], v153 offset:35840
	ds_read_b128 v[206:209], v153 offset:36864
	ds_read_b128 v[210:213], v153 offset:37888
	ds_read_b128 v[214:217], v153 offset:38912
	ds_read_b128 v[218:221], v153 offset:39936
	global_load_lds_dwordx4 v[228:229], off
	v_lshl_add_u64 v[228:229], s[14:15], 0, v[134:135]
	s_mov_b32 m0, s34
	s_nop 0
	global_load_lds_dwordx4 v[228:229], off
	s_waitcnt vmcnt(8)
	s_waitcnt lgkmcnt(0)
	v_mfma_f32_16x16x32_bf16 v[94:97], v[154:157], v[190:193], v[94:97]
	v_mfma_f32_16x16x32_bf16 v[102:105], v[166:169], v[190:193], v[102:105]
	v_mfma_f32_16x16x32_bf16 v[106:109], v[154:157], v[198:201], v[106:109]
	v_mfma_f32_16x16x32_bf16 v[110:113], v[166:169], v[198:201], v[110:113]
	v_mfma_f32_16x16x32_bf16 v[114:117], v[154:157], v[206:209], v[114:117]
	v_mfma_f32_16x16x32_bf16 v[122:125], v[166:169], v[206:209], v[122:125]
	v_mfma_f32_16x16x32_bf16 v[126:129], v[154:157], v[214:217], v[126:129]
	v_mfma_f32_16x16x32_bf16 v[118:121], v[166:169], v[214:217], v[118:121]
	s_barrier
	s_setprio 1
	s_waitcnt lgkmcnt(0)
	v_mfma_f32_16x16x32_bf16 v[94:97], v[158:161], v[194:197], v[94:97]
	v_mfma_f32_16x16x32_bf16 v[102:105], v[170:173], v[194:197], v[102:105]
	v_mfma_f32_16x16x32_bf16 v[106:109], v[158:161], v[202:205], v[106:109]
	v_mfma_f32_16x16x32_bf16 v[110:113], v[170:173], v[202:205], v[110:113]
	v_mfma_f32_16x16x32_bf16 v[114:117], v[158:161], v[210:213], v[114:117]
	v_mfma_f32_16x16x32_bf16 v[122:125], v[170:173], v[210:213], v[122:125]
	v_mfma_f32_16x16x32_bf16 v[126:129], v[158:161], v[218:221], v[126:129]
	v_mfma_f32_16x16x32_bf16 v[118:121], v[170:173], v[218:221], v[118:121]
	s_setprio 0
	s_setprio 1
	v_mfma_f32_16x16x32_bf16 v[90:93], v[174:177], v[190:193], v[90:93]
	v_mfma_f32_16x16x32_bf16 v[74:77], v[182:185], v[190:193], v[74:77]
	v_mfma_f32_16x16x32_bf16 v[78:81], v[174:177], v[198:201], v[78:81]
	v_mfma_f32_16x16x32_bf16 v[66:69], v[182:185], v[198:201], v[66:69]
	v_mfma_f32_16x16x32_bf16 v[98:101], v[174:177], v[206:209], v[98:101]
	v_mfma_f32_16x16x32_bf16 v[86:89], v[182:185], v[206:209], v[86:89]
	v_mfma_f32_16x16x32_bf16 v[82:85], v[174:177], v[214:217], v[82:85]
	v_mfma_f32_16x16x32_bf16 v[70:73], v[182:185], v[214:217], v[70:73]
	v_mfma_f32_16x16x32_bf16 v[90:93], v[178:181], v[194:197], v[90:93]
	v_mfma_f32_16x16x32_bf16 v[74:77], v[186:189], v[194:197], v[74:77]
	v_mfma_f32_16x16x32_bf16 v[78:81], v[178:181], v[202:205], v[78:81]
	v_mfma_f32_16x16x32_bf16 v[66:69], v[186:189], v[202:205], v[66:69]
	v_mfma_f32_16x16x32_bf16 v[98:101], v[178:181], v[210:213], v[98:101]
	v_mfma_f32_16x16x32_bf16 v[86:89], v[186:189], v[210:213], v[86:89]
	v_mfma_f32_16x16x32_bf16 v[82:85], v[178:181], v[218:221], v[82:85]
	v_mfma_f32_16x16x32_bf16 v[70:73], v[186:189], v[218:221], v[70:73]
	s_setprio 0
	s_barrier
; #define PG8_STAGE(bufoff, gbase, voff) do { _Pragma("unroll") for (int _i = 0; _i < 2; ++_i) \
;         __builtin_amdgcn_global_load_lds((const unsigned*)((const char*)(gbase) + (voff)[_i]), (PG8_LAS unsigned*)(lds + (bufoff) + ldsw + _i * 8192), 16, 0, 0); } while (0)
; #define PG8_LDA(dst, b, h) do { _Pragma("unroll") for (int m = 0; m < 4; ++m) _Pragma("unroll") for (int k = 0; k < 2; ++k) dst[m][k] = *(const PG8_LAS bf16x8*)(lds + PG8_SA(b, h) + aoff + m * 2048 + k * 1024); } while (0)
; #define PG8_MMA(ai, bj, At, Bt) do { __builtin_amdgcn_s_setprio(1); _Pragma("unroll") for (int m = 0; m < 4; ++m) _Pragma("unroll") for (int n = 0; n < 2; ++n) _Pragma("unroll") for (int k = 0; k < 2; ++k) \
;         acc[ai][bj][m][n] = __builtin_amdgcn_mfma_f32_16x16x32_bf16(Bt[n][k], At[m][k], acc[ai][bj][m][n], 0, 0, 0); __builtin_amdgcn_s_setprio(0); } while (0)
; #define PG8_WAIT_V(n) asm volatile("s_waitcnt vmcnt(" #n ")" ::: "memory")
; #define PG8_WAIT_L(n) asm volatile("s_waitcnt lgkmcnt(" #n ")" ::: "memory")
; #define PG8_BAR __builtin_amdgcn_s_barrier()
; #define PG8_SCHED __builtin_amdgcn_sched_barrier(0)
; template <class Epi, class Sched, bool ALIGN_EPI = false, bool SP2 = false>
; __device__ __forceinline__ void gemm_phase(PG8_LAS unsigned char* lds, const Gemm g, const Sched& S, const Epi& E) {
;     ...
;             PG8_LDA(At, 1, 1); PG8_STAGE(PG8_SB(1, 0), b3, voffB); PG8_STAGE(PG8_SB(1, 1), b3 + hstep, voffB); PG8_STAGE(PG8_SA(1, 0), a3, voffA);
;             PG8_WAIT_V(8); PG8_WAIT_L(0); PG8_BAR; PG8_MMA(1, 0, At, B0); PG8_MMA(1, 1, At, B1); PG8_BAR; PG8_SCHED;
;     ...
;         if (!has_next) break;
; #pragma unroll
;         for (int a = 0; a < 2; ++a)
; #pragma unroll
;             for (int b = 0; b < 2; ++b)
; #pragma unroll
;                 for (int m = 0; m < 4; ++m)
; #pragma unroll
;                     for (int n = 0; n < 2; ++n) acc[a][b][m][n] = (f32x4){0.f, 0.f, 0.f, 0.f};
;         cur = nxt; cA = nA; cB = nB; ++ui;
	s_add_i32 s14, s51, s21
	v_lshl_add_u64 v[162:163], v[162:163], 0, s[22:23]
	s_mov_b32 m0, s14
	ds_read_b128 v[190:193], v153 offset:49152
	ds_read_b128 v[194:197], v153 offset:50176
	ds_read_b128 v[198:201], v153 offset:51200
	ds_read_b128 v[202:205], v153 offset:52224
	ds_read_b128 v[206:209], v153 offset:53248
	ds_read_b128 v[210:213], v153 offset:54272
	ds_read_b128 v[214:217], v153 offset:55296
	ds_read_b128 v[218:221], v153 offset:56320
	global_load_lds_dwordx4 v[162:163], off
	s_add_i32 m0, s14, 0x2000
	s_add_u32 s2, s2, 0x40080
	v_lshl_add_u64 v[162:163], v[222:223], 0, s[22:23]
	s_addc_u32 s3, s3, 0
	s_add_i32 s14, s52, s21
	global_load_lds_dwordx4 v[162:163], off
	v_lshl_add_u64 v[162:163], s[2:3], 0, v[132:133]
	s_mov_b32 m0, s14
	s_nop 0
	global_load_lds_dwordx4 v[162:163], off
	v_lshl_add_u64 v[162:163], s[2:3], 0, v[136:137]
	s_add_i32 m0, s14, 0x2000
	s_nop 0
	global_load_lds_dwordx4 v[162:163], off
	v_lshl_add_u64 v[162:163], v[224:225], 0, s[22:23]
	s_mov_b32 m0, s37
	s_nop 0
	global_load_lds_dwordx4 v[162:163], off
	v_lshl_add_u64 v[162:163], v[226:227], 0, s[22:23]
	s_mov_b32 m0, s42
	s_nop 0
	global_load_lds_dwordx4 v[162:163], off
	s_waitcnt vmcnt(8)
	s_waitcnt lgkmcnt(0)
	v_mfma_f32_16x16x32_bf16 v[62:65], v[154:157], v[190:193], v[62:65]
	v_mfma_f32_16x16x32_bf16 v[58:61], v[166:169], v[190:193], v[58:61]
	v_mfma_f32_16x16x32_bf16 v[46:49], v[154:157], v[198:201], v[46:49]
	v_mfma_f32_16x16x32_bf16 v[42:45], v[166:169], v[198:201], v[42:45]
	v_mfma_f32_16x16x32_bf16 v[30:33], v[154:157], v[206:209], v[30:33]
	v_mfma_f32_16x16x32_bf16 v[26:29], v[166:169], v[206:209], v[26:29]
	v_mfma_f32_16x16x32_bf16 v[14:17], v[154:157], v[214:217], v[14:17]
	v_mfma_f32_16x16x32_bf16 v[10:13], v[166:169], v[214:217], v[10:13]
	s_barrier
	s_setprio 1
	s_waitcnt lgkmcnt(0)
	v_mfma_f32_16x16x32_bf16 v[62:65], v[158:161], v[194:197], v[62:65]
	v_mfma_f32_16x16x32_bf16 v[58:61], v[170:173], v[194:197], v[58:61]
	v_mfma_f32_16x16x32_bf16 v[46:49], v[158:161], v[202:205], v[46:49]
	v_mfma_f32_16x16x32_bf16 v[42:45], v[170:173], v[202:205], v[42:45]
	v_mfma_f32_16x16x32_bf16 v[30:33], v[158:161], v[210:213], v[30:33]
	v_mfma_f32_16x16x32_bf16 v[26:29], v[170:173], v[210:213], v[26:29]
	v_mfma_f32_16x16x32_bf16 v[14:17], v[158:161], v[218:221], v[14:17]
	v_mfma_f32_16x16x32_bf16 v[10:13], v[170:173], v[218:221], v[10:13]
	s_setprio 0
	s_setprio 1
	v_mfma_f32_16x16x32_bf16 v[54:57], v[174:177], v[190:193], v[54:57]
	v_mfma_f32_16x16x32_bf16 v[50:53], v[182:185], v[190:193], v[50:53]
	v_mfma_f32_16x16x32_bf16 v[38:41], v[174:177], v[198:201], v[38:41]
	v_mfma_f32_16x16x32_bf16 v[34:37], v[182:185], v[198:201], v[34:37]
	v_mfma_f32_16x16x32_bf16 v[22:25], v[174:177], v[206:209], v[22:25]
	v_mfma_f32_16x16x32_bf16 v[18:21], v[182:185], v[206:209], v[18:21]
	v_mfma_f32_16x16x32_bf16 v[6:9], v[174:177], v[214:217], v[6:9]
	v_mfma_f32_16x16x32_bf16 v[2:5], v[182:185], v[214:217], v[2:5]
	v_mfma_f32_16x16x32_bf16 v[54:57], v[178:181], v[194:197], v[54:57]
	v_mfma_f32_16x16x32_bf16 v[50:53], v[186:189], v[194:197], v[50:53]
	v_mfma_f32_16x16x32_bf16 v[38:41], v[178:181], v[202:205], v[38:41]
	v_mfma_f32_16x16x32_bf16 v[34:37], v[186:189], v[202:205], v[34:37]
	v_mfma_f32_16x16x32_bf16 v[22:25], v[178:181], v[210:213], v[22:25]
	v_mfma_f32_16x16x32_bf16 v[18:21], v[186:189], v[210:213], v[18:21]
	v_mfma_f32_16x16x32_bf16 v[6:9], v[178:181], v[218:221], v[6:9]
	v_mfma_f32_16x16x32_bf16 v[2:5], v[186:189], v[218:221], v[2:5]
	s_setprio 0
	s_barrier
	s_add_i32 s50, s50, 2
	s_add_u32 s40, s40, 0x100
	s_addc_u32 s41, s41, 0
	s_cmp_gt_u32 s50, 13
	s_cbranch_scc0 .LBB0_1488
	s_add_u32 s2, s46, 0xffffff00
	s_addc_u32 s3, s47, -1
	s_andn2_b64 vcc, exec, s[8:9]
	s_cbranch_vccnz .LBB0_1491
	v_mov_b32_e32 v2, 0
	s_mov_b32 s20, s24
	s_mov_b32 s12, s28
	s_mov_b64 s[0:1], s[38:39]
	s_mov_b32 s36, s45
	v_mov_b32_e32 v3, v2
	v_mov_b64_e32 v[4:5], v[2:3]
	v_mov_b64_e32 v[6:7], v[2:3]
	v_mov_b64_e32 v[8:9], v[2:3]
	v_mov_b64_e32 v[18:19], v[2:3]
	v_mov_b64_e32 v[20:21], v[2:3]
	v_mov_b64_e32 v[22:23], v[2:3]
	v_mov_b64_e32 v[24:25], v[2:3]
	v_mov_b64_e32 v[34:35], v[2:3]
	v_mov_b64_e32 v[36:37], v[2:3]
	v_mov_b64_e32 v[38:39], v[2:3]
	v_mov_b64_e32 v[40:41], v[2:3]
	v_mov_b64_e32 v[50:51], v[2:3]
	v_mov_b64_e32 v[52:53], v[2:3]
	v_mov_b64_e32 v[54:55], v[2:3]
	v_mov_b64_e32 v[56:57], v[2:3]
	v_mov_b64_e32 v[10:11], v[2:3]
	v_mov_b64_e32 v[12:13], v[2:3]
	v_mov_b64_e32 v[14:15], v[2:3]
	v_mov_b64_e32 v[16:17], v[2:3]
	v_mov_b64_e32 v[26:27], v[2:3]
	v_mov_b64_e32 v[28:29], v[2:3]
	v_mov_b64_e32 v[30:31], v[2:3]
	v_mov_b64_e32 v[32:33], v[2:3]
	v_mov_b64_e32 v[42:43], v[2:3]
	v_mov_b64_e32 v[44:45], v[2:3]
	v_mov_b64_e32 v[46:47], v[2:3]
	v_mov_b64_e32 v[48:49], v[2:3]
	v_mov_b64_e32 v[58:59], v[2:3]
	v_mov_b64_e32 v[60:61], v[2:3]
	v_mov_b64_e32 v[62:63], v[2:3]
	v_mov_b64_e32 v[64:65], v[2:3]
	v_mov_b64_e32 v[70:71], v[2:3]
	v_mov_b64_e32 v[72:73], v[2:3]
	v_mov_b64_e32 v[82:83], v[2:3]
	v_mov_b64_e32 v[84:85], v[2:3]
	v_mov_b64_e32 v[86:87], v[2:3]
	v_mov_b64_e32 v[88:89], v[2:3]
	v_mov_b64_e32 v[98:99], v[2:3]
	v_mov_b64_e32 v[100:101], v[2:3]
	v_mov_b64_e32 v[66:67], v[2:3]
	v_mov_b64_e32 v[68:69], v[2:3]
	v_mov_b64_e32 v[78:79], v[2:3]
	v_mov_b64_e32 v[80:81], v[2:3]
	v_mov_b64_e32 v[74:75], v[2:3]
	v_mov_b64_e32 v[76:77], v[2:3]
	v_mov_b64_e32 v[90:91], v[2:3]
	v_mov_b64_e32 v[92:93], v[2:3]
	v_mov_b64_e32 v[118:119], v[2:3]
	v_mov_b64_e32 v[120:121], v[2:3]
	v_mov_b64_e32 v[126:127], v[2:3]
	v_mov_b64_e32 v[128:129], v[2:3]
	v_mov_b64_e32 v[122:123], v[2:3]
	v_mov_b64_e32 v[124:125], v[2:3]
	v_mov_b64_e32 v[114:115], v[2:3]
	v_mov_b64_e32 v[116:117], v[2:3]
	v_mov_b64_e32 v[110:111], v[2:3]
	v_mov_b64_e32 v[112:113], v[2:3]
	v_mov_b64_e32 v[106:107], v[2:3]
	v_mov_b64_e32 v[108:109], v[2:3]
	v_mov_b64_e32 v[102:103], v[2:3]
	v_mov_b64_e32 v[104:105], v[2:3]
	v_mov_b64_e32 v[94:95], v[2:3]
	v_mov_b64_e32 v[96:97], v[2:3]
	s_branch .LBB0_1492

; #define PG8_STAGE(bufoff, gbase, voff) do { _Pragma("unroll") for (int _i = 0; _i < 2; ++_i) \
;         __builtin_amdgcn_global_load_lds((const unsigned*)((const char*)(gbase) + (voff)[_i]), (PG8_LAS unsigned*)(lds + (bufoff) + ldsw + _i * 8192), 16, 0, 0); } while (0)
; #define PG8_LDA(dst, b, h) do { _Pragma("unroll") for (int m = 0; m < 4; ++m) _Pragma("unroll") for (int k = 0; k < 2; ++k) dst[m][k] = *(const PG8_LAS bf16x8*)(lds + PG8_SA(b, h) + aoff + m * 2048 + k * 1024); } while (0)
; #define PG8_LDB(dst, b, h) do { _Pragma("unroll") for (int n = 0; n < 2; ++n) _Pragma("unroll") for (int k = 0; k < 2; ++k) dst[n][k] = *(const PG8_LAS bf16x8*)(lds + PG8_SB(b, h) + boff + n * 2048 + k * 1024); } while (0)
; #define PG8_MMA(ai, bj, At, Bt) do { __builtin_amdgcn_s_setprio(1); _Pragma("unroll") for (int m = 0; m < 4; ++m) _Pragma("unroll") for (int n = 0; n < 2; ++n) _Pragma("unroll") for (int k = 0; k < 2; ++k) \
;         acc[ai][bj][m][n] = __builtin_amdgcn_mfma_f32_16x16x32_bf16(Bt[n][k], At[m][k], acc[ai][bj][m][n], 0, 0, 0); __builtin_amdgcn_s_setprio(0); } while (0)
; #define PG8_WAIT_V(n) asm volatile("s_waitcnt vmcnt(" #n ")" ::: "memory")
; #define PG8_WAIT_L(n) asm volatile("s_waitcnt lgkmcnt(" #n ")" ::: "memory")
; template <class Epi, class Sched, bool ALIGN_EPI = false, bool SP2 = false>
; __device__ __forceinline__ void gemm_phase(PG8_LAS unsigned char* lds, const Gemm g, const Sched& S, const Epi& E) {
;     ...
;             const bool last = (t == nt - 2);
;             const char* a1 = cA + (size_t)(t + 1) * kstep;
;             const char* a2 = last ? nA : cA + (size_t)(t + 2) * kstep; const char* b2 = last ? nB : cB + (size_t)(t + 2) * kstep;
;             const char* a3 = a2 + kstep; const char* b3 = b2 + kstep;
;             if (last && has_next) S.a_ready(nxt);
;             if constexpr (SP2) {
;             PG8_LDB(B0, 0, 0); PG8_LDB(B1, 0, 1); PG8_SCHED; PG8_LDA(At, 0, 0); PG8_STAGE(PG8_SA(1, 1), a1 + hstep, voffA);
;             PG8_WAIT_V(8); PG8_WAIT_L(0); PG8_BAR; PG8_MMA(0, 0, At, B0); PG8_MMA(0, 1, At, B1); PG8_BAR; PG8_SCHED;
;             PG8_LDA(At, 0, 1); PG8_STAGE(PG8_SB(0, 0), b2, voffB); PG8_STAGE(PG8_SB(0, 1), b2 + hstep, voffB); PG8_STAGE(PG8_SA(0, 0), a2, voffA);
;             PG8_WAIT_V(8); PG8_WAIT_L(0); PG8_BAR; PG8_MMA(1, 0, At, B0); PG8_MMA(1, 1, At, B1); PG8_BAR; PG8_SCHED;
.LBB0_1628:
	ds_read_b128 v[146:149], v153
	ds_read_b128 v[156:159], v153 offset:1024
	ds_read_b128 v[160:163], v153 offset:2048
	ds_read_b128 v[164:167], v153 offset:3072
	ds_read_b128 v[168:171], v154
	ds_read_b128 v[172:175], v154 offset:1024
	ds_read_b128 v[176:179], v154 offset:2048
	ds_read_b128 v[180:183], v154 offset:3072
	s_add_u32 s2, s36, 0xfffc0080
	s_addc_u32 s3, s37, -1
	s_cmp_eq_u32 s48, 12
	s_cselect_b32 s15, s23, s3
	s_cselect_b32 s14, s46, s2
	s_cselect_b32 s3, s21, s35
	s_cselect_b32 s2, s47, s34
	v_lshl_add_u64 v[216:217], s[36:37], 0, v[138:139]
	s_add_i32 m0, s26, 0xc000
	ds_read_b128 v[184:187], v155
	ds_read_b128 v[188:191], v155 offset:1024
	ds_read_b128 v[192:195], v155 offset:2048
	ds_read_b128 v[196:199], v155 offset:3072
	ds_read_b128 v[200:203], v155 offset:4096
	ds_read_b128 v[204:207], v155 offset:5120
	ds_read_b128 v[208:211], v155 offset:6144
	ds_read_b128 v[212:215], v155 offset:7168
	global_load_lds_dwordx4 v[216:217], off
	v_lshl_add_u64 v[216:217], s[36:37], 0, v[140:141]
	s_add_i32 m0, s26, 0xe000
	s_nop 0
	global_load_lds_dwordx4 v[216:217], off
	s_waitcnt vmcnt(8)
	s_waitcnt lgkmcnt(0)
	v_mfma_f32_16x16x32_bf16 v[126:129], v[146:149], v[184:187], v[126:129]
	v_mfma_f32_16x16x32_bf16 v[122:125], v[160:163], v[184:187], v[122:125]
	v_mfma_f32_16x16x32_bf16 v[110:113], v[146:149], v[192:195], v[110:113]
	v_mfma_f32_16x16x32_bf16 v[106:109], v[160:163], v[192:195], v[106:109]
	v_mfma_f32_16x16x32_bf16 v[94:97], v[146:149], v[200:203], v[94:97]
	v_mfma_f32_16x16x32_bf16 v[90:93], v[160:163], v[200:203], v[90:93]
	v_mfma_f32_16x16x32_bf16 v[78:81], v[146:149], v[208:211], v[78:81]
	v_mfma_f32_16x16x32_bf16 v[74:77], v[160:163], v[208:211], v[74:77]
	s_barrier
	s_setprio 1
	s_waitcnt lgkmcnt(0)
	v_mfma_f32_16x16x32_bf16 v[126:129], v[156:159], v[188:191], v[126:129]
	v_mfma_f32_16x16x32_bf16 v[122:125], v[164:167], v[188:191], v[122:125]
	v_mfma_f32_16x16x32_bf16 v[110:113], v[156:159], v[196:199], v[110:113]
	v_mfma_f32_16x16x32_bf16 v[106:109], v[164:167], v[196:199], v[106:109]
	v_mfma_f32_16x16x32_bf16 v[94:97], v[156:159], v[204:207], v[94:97]
	v_mfma_f32_16x16x32_bf16 v[90:93], v[164:167], v[204:207], v[90:93]
	v_mfma_f32_16x16x32_bf16 v[78:81], v[156:159], v[212:215], v[78:81]
	v_mfma_f32_16x16x32_bf16 v[74:77], v[164:167], v[212:215], v[74:77]
	s_setprio 0
	s_setprio 1
	v_mfma_f32_16x16x32_bf16 v[118:121], v[168:171], v[184:187], v[118:121]
	v_mfma_f32_16x16x32_bf16 v[114:117], v[176:179], v[184:187], v[114:117]
	v_mfma_f32_16x16x32_bf16 v[102:105], v[168:171], v[192:195], v[102:105]
	v_mfma_f32_16x16x32_bf16 v[98:101], v[176:179], v[192:195], v[98:101]
	v_mfma_f32_16x16x32_bf16 v[86:89], v[168:171], v[200:203], v[86:89]
	v_mfma_f32_16x16x32_bf16 v[82:85], v[176:179], v[200:203], v[82:85]
	v_mfma_f32_16x16x32_bf16 v[70:73], v[168:171], v[208:211], v[70:73]
	v_mfma_f32_16x16x32_bf16 v[66:69], v[176:179], v[208:211], v[66:69]
	v_mfma_f32_16x16x32_bf16 v[118:121], v[172:175], v[188:191], v[118:121]
	v_mfma_f32_16x16x32_bf16 v[114:117], v[180:183], v[188:191], v[114:117]
	v_mfma_f32_16x16x32_bf16 v[102:105], v[172:175], v[196:199], v[102:105]
	v_mfma_f32_16x16x32_bf16 v[98:101], v[180:183], v[196:199], v[98:101]
	v_mfma_f32_16x16x32_bf16 v[86:89], v[172:175], v[204:207], v[86:89]
	v_mfma_f32_16x16x32_bf16 v[82:85], v[180:183], v[204:207], v[82:85]
	v_mfma_f32_16x16x32_bf16 v[70:73], v[172:175], v[212:215], v[70:73]
	v_mfma_f32_16x16x32_bf16 v[66:69], v[180:183], v[212:215], v[66:69]
	s_setprio 0
	s_barrier
	s_add_i32 s49, s42, s17
	v_lshl_add_u64 v[216:217], s[2:3], 0, v[132:133]
	s_mov_b32 m0, s49
	ds_read_b128 v[184:187], v155 offset:16384
	ds_read_b128 v[188:191], v155 offset:17408
	ds_read_b128 v[192:195], v155 offset:18432
	ds_read_b128 v[196:199], v155 offset:19456
	ds_read_b128 v[200:203], v155 offset:20480
	ds_read_b128 v[204:207], v155 offset:21504
	ds_read_b128 v[208:211], v155 offset:22528
	ds_read_b128 v[212:215], v155 offset:23552
	global_load_lds_dwordx4 v[216:217], off
	s_add_i32 m0, s49, 0x2000
	s_add_u32 s50, s2, 0x40000
	v_lshl_add_u64 v[218:219], s[2:3], 0, v[136:137]
	s_addc_u32 s51, s3, 0
	s_add_i32 s49, s43, s17
	global_load_lds_dwordx4 v[218:219], off
	v_lshl_add_u64 v[220:221], s[50:51], 0, v[132:133]
	s_mov_b32 m0, s49
	v_lshl_add_u64 v[222:223], s[14:15], 0, v[134:135]
	global_load_lds_dwordx4 v[220:221], off
	v_lshl_add_u64 v[220:221], s[50:51], 0, v[136:137]
	s_add_i32 m0, s49, 0x2000
	s_nop 0
	global_load_lds_dwordx4 v[220:221], off
	v_lshl_add_u64 v[220:221], s[14:15], 0, v[130:131]
	s_mov_b32 m0, s26
	s_nop 0
	global_load_lds_dwordx4 v[220:221], off
	s_mov_b32 m0, s27
	s_nop 0
	global_load_lds_dwordx4 v[222:223], off
	s_waitcnt vmcnt(8)
	s_waitcnt lgkmcnt(0)
	v_mfma_f32_16x16x32_bf16 v[62:65], v[146:149], v[184:187], v[62:65]
	v_mfma_f32_16x16x32_bf16 v[58:61], v[160:163], v[184:187], v[58:61]
	v_mfma_f32_16x16x32_bf16 v[46:49], v[146:149], v[192:195], v[46:49]
	v_mfma_f32_16x16x32_bf16 v[42:45], v[160:163], v[192:195], v[42:45]
	v_mfma_f32_16x16x32_bf16 v[30:33], v[146:149], v[200:203], v[30:33]
	v_mfma_f32_16x16x32_bf16 v[26:29], v[160:163], v[200:203], v[26:29]
	v_mfma_f32_16x16x32_bf16 v[14:17], v[146:149], v[208:211], v[14:17]
	v_mfma_f32_16x16x32_bf16 v[10:13], v[160:163], v[208:211], v[10:13]
	s_barrier
; #define PG8_STAGE(bufoff, gbase, voff) do { _Pragma("unroll") for (int _i = 0; _i < 2; ++_i) \
;         __builtin_amdgcn_global_load_lds((const unsigned*)((const char*)(gbase) + (voff)[_i]), (PG8_LAS unsigned*)(lds + (bufoff) + ldsw + _i * 8192), 16, 0, 0); } while (0)
; #define PG8_LDA(dst, b, h) do { _Pragma("unroll") for (int m = 0; m < 4; ++m) _Pragma("unroll") for (int k = 0; k < 2; ++k) dst[m][k] = *(const PG8_LAS bf16x8*)(lds + PG8_SA(b, h) + aoff + m * 2048 + k * 1024); } while (0)
; #define PG8_LDB(dst, b, h) do { _Pragma("unroll") for (int n = 0; n < 2; ++n) _Pragma("unroll") for (int k = 0; k < 2; ++k) dst[n][k] = *(const PG8_LAS bf16x8*)(lds + PG8_SB(b, h) + boff + n * 2048 + k * 1024); } while (0)
; #define PG8_MMA(ai, bj, At, Bt) do { __builtin_amdgcn_s_setprio(1); _Pragma("unroll") for (int m = 0; m < 4; ++m) _Pragma("unroll") for (int n = 0; n < 2; ++n) _Pragma("unroll") for (int k = 0; k < 2; ++k) \
;         acc[ai][bj][m][n] = __builtin_amdgcn_mfma_f32_16x16x32_bf16(Bt[n][k], At[m][k], acc[ai][bj][m][n], 0, 0, 0); __builtin_amdgcn_s_setprio(0); } while (0)
; #define PG8_WAIT_V(n) asm volatile("s_waitcnt vmcnt(" #n ")" ::: "memory")
; #define PG8_WAIT_L(n) asm volatile("s_waitcnt lgkmcnt(" #n ")" ::: "memory")
; #define PG8_BAR __builtin_amdgcn_s_barrier()
; #define PG8_SCHED __builtin_amdgcn_sched_barrier(0)
; template <class Epi, class Sched, bool ALIGN_EPI = false, bool SP2 = false>
; __device__ __forceinline__ void gemm_phase(PG8_LAS unsigned char* lds, const Gemm g, const Sched& S, const Epi& E) {
;     ...
;             PG8_WAIT_V(8); PG8_WAIT_L(0); PG8_BAR; PG8_MMA(1, 0, At, B0); PG8_MMA(1, 1, At, B1); PG8_BAR; PG8_SCHED;
;             PG8_LDB(B0, 1, 0); PG8_LDB(B1, 1, 1); PG8_SCHED; PG8_LDA(At, 1, 0); PG8_STAGE(PG8_SA(0, 1), a2 + hstep, voffA);
;             PG8_WAIT_V(8); PG8_WAIT_L(0); PG8_BAR; PG8_MMA(0, 0, At, B0); PG8_MMA(0, 1, At, B1); PG8_BAR; PG8_SCHED;
	s_setprio 1
	s_waitcnt lgkmcnt(0)
	v_mfma_f32_16x16x32_bf16 v[62:65], v[156:159], v[188:191], v[62:65]
	v_mfma_f32_16x16x32_bf16 v[58:61], v[164:167], v[188:191], v[58:61]
	v_mfma_f32_16x16x32_bf16 v[46:49], v[156:159], v[196:199], v[46:49]
	v_mfma_f32_16x16x32_bf16 v[42:45], v[164:167], v[196:199], v[42:45]
	v_mfma_f32_16x16x32_bf16 v[30:33], v[156:159], v[204:207], v[30:33]
	v_mfma_f32_16x16x32_bf16 v[26:29], v[164:167], v[204:207], v[26:29]
	v_mfma_f32_16x16x32_bf16 v[14:17], v[156:159], v[212:215], v[14:17]
	v_mfma_f32_16x16x32_bf16 v[10:13], v[164:167], v[212:215], v[10:13]
	s_setprio 0
	s_setprio 1
	v_mfma_f32_16x16x32_bf16 v[54:57], v[168:171], v[184:187], v[54:57]
	v_mfma_f32_16x16x32_bf16 v[50:53], v[176:179], v[184:187], v[50:53]
	v_mfma_f32_16x16x32_bf16 v[38:41], v[168:171], v[192:195], v[38:41]
	v_mfma_f32_16x16x32_bf16 v[34:37], v[176:179], v[192:195], v[34:37]
	v_mfma_f32_16x16x32_bf16 v[22:25], v[168:171], v[200:203], v[22:25]
	v_mfma_f32_16x16x32_bf16 v[18:21], v[176:179], v[200:203], v[18:21]
	v_mfma_f32_16x16x32_bf16 v[6:9], v[168:171], v[208:211], v[6:9]
	v_mfma_f32_16x16x32_bf16 v[2:5], v[176:179], v[208:211], v[2:5]
	v_mfma_f32_16x16x32_bf16 v[54:57], v[172:175], v[188:191], v[54:57]
	v_mfma_f32_16x16x32_bf16 v[50:53], v[180:183], v[188:191], v[50:53]
	v_mfma_f32_16x16x32_bf16 v[38:41], v[172:175], v[196:199], v[38:41]
	v_mfma_f32_16x16x32_bf16 v[34:37], v[180:183], v[196:199], v[34:37]
	v_mfma_f32_16x16x32_bf16 v[22:25], v[172:175], v[204:207], v[22:25]
	v_mfma_f32_16x16x32_bf16 v[18:21], v[180:183], v[204:207], v[18:21]
	v_mfma_f32_16x16x32_bf16 v[6:9], v[172:175], v[212:215], v[6:9]
	v_mfma_f32_16x16x32_bf16 v[2:5], v[180:183], v[212:215], v[2:5]
	s_setprio 0
	s_barrier
	s_add_i32 s49, 0, 0x18000
	s_add_i32 s50, 0, 0x1c000
	v_add_u32_e32 v164, s49, v151
	v_add_u32_e32 v180, s50, v151
	ds_read_b128 v[146:149], v164
	ds_read_b128 v[156:159], v164 offset:1024
	ds_read_b128 v[160:163], v164 offset:2048
	ds_read_b128 v[164:167], v164 offset:3072
	ds_read_b128 v[168:171], v180
	ds_read_b128 v[172:175], v180 offset:1024
	ds_read_b128 v[176:179], v180 offset:2048
	ds_read_b128 v[180:183], v180 offset:3072
	s_add_u32 s14, s14, 0x40000
	s_addc_u32 s15, s15, 0
	s_mov_b32 m0, s31
	v_lshl_add_u64 v[224:225], s[14:15], 0, v[130:131]
	ds_read_b128 v[184:187], v155 offset:32768
	ds_read_b128 v[188:191], v155 offset:33792
	ds_read_b128 v[192:195], v155 offset:34816
	ds_read_b128 v[196:199], v155 offset:35840
	ds_read_b128 v[200:203], v155 offset:36864
	ds_read_b128 v[204:207], v155 offset:37888
	ds_read_b128 v[208:211], v155 offset:38912
	ds_read_b128 v[212:215], v155 offset:39936
	global_load_lds_dwordx4 v[224:225], off
	v_lshl_add_u64 v[224:225], s[14:15], 0, v[134:135]
	s_mov_b32 m0, s33
	s_nop 0
	global_load_lds_dwordx4 v[224:225], off
	s_waitcnt vmcnt(8)
	s_waitcnt lgkmcnt(0)
	v_mfma_f32_16x16x32_bf16 v[126:129], v[146:149], v[184:187], v[126:129]
	v_mfma_f32_16x16x32_bf16 v[122:125], v[160:163], v[184:187], v[122:125]
	v_mfma_f32_16x16x32_bf16 v[110:113], v[146:149], v[192:195], v[110:113]
	v_mfma_f32_16x16x32_bf16 v[106:109], v[160:163], v[192:195], v[106:109]
	v_mfma_f32_16x16x32_bf16 v[94:97], v[146:149], v[200:203], v[94:97]
	v_mfma_f32_16x16x32_bf16 v[90:93], v[160:163], v[200:203], v[90:93]
	v_mfma_f32_16x16x32_bf16 v[78:81], v[146:149], v[208:211], v[78:81]
	v_mfma_f32_16x16x32_bf16 v[74:77], v[160:163], v[208:211], v[74:77]
	s_barrier
	s_setprio 1
	s_waitcnt lgkmcnt(0)
	v_mfma_f32_16x16x32_bf16 v[126:129], v[156:159], v[188:191], v[126:129]
	v_mfma_f32_16x16x32_bf16 v[122:125], v[164:167], v[188:191], v[122:125]
	v_mfma_f32_16x16x32_bf16 v[110:113], v[156:159], v[196:199], v[110:113]
	v_mfma_f32_16x16x32_bf16 v[106:109], v[164:167], v[196:199], v[106:109]
	v_mfma_f32_16x16x32_bf16 v[94:97], v[156:159], v[204:207], v[94:97]
	v_mfma_f32_16x16x32_bf16 v[90:93], v[164:167], v[204:207], v[90:93]
	v_mfma_f32_16x16x32_bf16 v[78:81], v[156:159], v[212:215], v[78:81]
	v_mfma_f32_16x16x32_bf16 v[74:77], v[164:167], v[212:215], v[74:77]
	s_setprio 0
	s_setprio 1
	v_mfma_f32_16x16x32_bf16 v[118:121], v[168:171], v[184:187], v[118:121]
	v_mfma_f32_16x16x32_bf16 v[114:117], v[176:179], v[184:187], v[114:117]
	v_mfma_f32_16x16x32_bf16 v[102:105], v[168:171], v[192:195], v[102:105]
	v_mfma_f32_16x16x32_bf16 v[98:101], v[176:179], v[192:195], v[98:101]
	v_mfma_f32_16x16x32_bf16 v[86:89], v[168:171], v[200:203], v[86:89]
	v_mfma_f32_16x16x32_bf16 v[82:85], v[176:179], v[200:203], v[82:85]
	v_mfma_f32_16x16x32_bf16 v[70:73], v[168:171], v[208:211], v[70:73]
	v_mfma_f32_16x16x32_bf16 v[66:69], v[176:179], v[208:211], v[66:69]
	v_mfma_f32_16x16x32_bf16 v[118:121], v[172:175], v[188:191], v[118:121]
	v_mfma_f32_16x16x32_bf16 v[114:117], v[180:183], v[188:191], v[114:117]
	v_mfma_f32_16x16x32_bf16 v[102:105], v[172:175], v[196:199], v[102:105]
	v_mfma_f32_16x16x32_bf16 v[98:101], v[180:183], v[196:199], v[98:101]
	v_mfma_f32_16x16x32_bf16 v[86:89], v[172:175], v[204:207], v[86:89]
	v_mfma_f32_16x16x32_bf16 v[82:85], v[180:183], v[204:207], v[82:85]
	v_mfma_f32_16x16x32_bf16 v[70:73], v[172:175], v[212:215], v[70:73]
	v_mfma_f32_16x16x32_bf16 v[66:69], v[180:183], v[212:215], v[66:69]
	s_setprio 0
	s_barrier
; #define PG8_STAGE(bufoff, gbase, voff) do { _Pragma("unroll") for (int _i = 0; _i < 2; ++_i) \
;         __builtin_amdgcn_global_load_lds((const unsigned*)((const char*)(gbase) + (voff)[_i]), (PG8_LAS unsigned*)(lds + (bufoff) + ldsw + _i * 8192), 16, 0, 0); } while (0)
; #define PG8_LDA(dst, b, h) do { _Pragma("unroll") for (int m = 0; m < 4; ++m) _Pragma("unroll") for (int k = 0; k < 2; ++k) dst[m][k] = *(const PG8_LAS bf16x8*)(lds + PG8_SA(b, h) + aoff + m * 2048 + k * 1024); } while (0)
; #define PG8_MMA(ai, bj, At, Bt) do { __builtin_amdgcn_s_setprio(1); _Pragma("unroll") for (int m = 0; m < 4; ++m) _Pragma("unroll") for (int n = 0; n < 2; ++n) _Pragma("unroll") for (int k = 0; k < 2; ++k) \
;         acc[ai][bj][m][n] = __builtin_amdgcn_mfma_f32_16x16x32_bf16(Bt[n][k], At[m][k], acc[ai][bj][m][n], 0, 0, 0); __builtin_amdgcn_s_setprio(0); } while (0)
; #define PG8_WAIT_V(n) asm volatile("s_waitcnt vmcnt(" #n ")" ::: "memory")
; #define PG8_WAIT_L(n) asm volatile("s_waitcnt lgkmcnt(" #n ")" ::: "memory")
; #define PG8_BAR __builtin_amdgcn_s_barrier()
; #define PG8_SCHED __builtin_amdgcn_sched_barrier(0)
; template <class Epi, class Sched, bool ALIGN_EPI = false, bool SP2 = false>
; __device__ __forceinline__ void gemm_phase(PG8_LAS unsigned char* lds, const Gemm g, const Sched& S, const Epi& E) {
;     ...
;             PG8_LDA(At, 1, 1); PG8_STAGE(PG8_SB(1, 0), b3, voffB); PG8_STAGE(PG8_SB(1, 1), b3 + hstep, voffB); PG8_STAGE(PG8_SA(1, 0), a3, voffA);
;             PG8_WAIT_V(8); PG8_WAIT_L(0); PG8_BAR; PG8_MMA(1, 0, At, B0); PG8_MMA(1, 1, At, B1); PG8_BAR; PG8_SCHED;
;     ...
;         if constexpr (ALIGN_EPI) { if (wr == 0) PG8_BAR; }
	s_add_i32 s14, s49, s17
	v_lshl_add_u64 v[216:217], v[216:217], 0, s[12:13]
	s_mov_b32 m0, s14
	ds_read_b128 v[184:187], v155 offset:49152
	ds_read_b128 v[188:191], v155 offset:50176
	ds_read_b128 v[192:195], v155 offset:51200
	ds_read_b128 v[196:199], v155 offset:52224
	ds_read_b128 v[200:203], v155 offset:53248
	ds_read_b128 v[204:207], v155 offset:54272
	ds_read_b128 v[208:211], v155 offset:55296
	ds_read_b128 v[212:215], v155 offset:56320
	global_load_lds_dwordx4 v[216:217], off
	s_add_i32 m0, s14, 0x2000
	s_add_u32 s2, s2, 0x40080
	v_lshl_add_u64 v[216:217], v[218:219], 0, s[12:13]
	s_addc_u32 s3, s3, 0
	s_add_i32 s14, s50, s17
	global_load_lds_dwordx4 v[216:217], off
	v_lshl_add_u64 v[216:217], s[2:3], 0, v[132:133]
	s_mov_b32 m0, s14
	s_nop 0
	global_load_lds_dwordx4 v[216:217], off
	v_lshl_add_u64 v[216:217], s[2:3], 0, v[136:137]
	s_add_i32 m0, s14, 0x2000
	s_nop 0
	global_load_lds_dwordx4 v[216:217], off
	v_lshl_add_u64 v[216:217], v[220:221], 0, s[12:13]
	s_mov_b32 m0, s39
	s_nop 0
	global_load_lds_dwordx4 v[216:217], off
	v_lshl_add_u64 v[216:217], v[222:223], 0, s[12:13]
	s_mov_b32 m0, s40
	s_nop 0
	global_load_lds_dwordx4 v[216:217], off
	s_waitcnt vmcnt(8)
	s_waitcnt lgkmcnt(0)
	v_mfma_f32_16x16x32_bf16 v[62:65], v[146:149], v[184:187], v[62:65]
	v_mfma_f32_16x16x32_bf16 v[58:61], v[160:163], v[184:187], v[58:61]
	v_mfma_f32_16x16x32_bf16 v[46:49], v[146:149], v[192:195], v[46:49]
	v_mfma_f32_16x16x32_bf16 v[42:45], v[160:163], v[192:195], v[42:45]
	v_mfma_f32_16x16x32_bf16 v[30:33], v[146:149], v[200:203], v[30:33]
	v_mfma_f32_16x16x32_bf16 v[26:29], v[160:163], v[200:203], v[26:29]
	v_mfma_f32_16x16x32_bf16 v[14:17], v[146:149], v[208:211], v[14:17]
	v_mfma_f32_16x16x32_bf16 v[10:13], v[160:163], v[208:211], v[10:13]
	s_barrier
	s_setprio 1
	s_waitcnt lgkmcnt(0)
	v_mfma_f32_16x16x32_bf16 v[62:65], v[156:159], v[188:191], v[62:65]
	v_mfma_f32_16x16x32_bf16 v[58:61], v[164:167], v[188:191], v[58:61]
	v_mfma_f32_16x16x32_bf16 v[46:49], v[156:159], v[196:199], v[46:49]
	v_mfma_f32_16x16x32_bf16 v[42:45], v[164:167], v[196:199], v[42:45]
	v_mfma_f32_16x16x32_bf16 v[30:33], v[156:159], v[204:207], v[30:33]
	v_mfma_f32_16x16x32_bf16 v[26:29], v[164:167], v[204:207], v[26:29]
	v_mfma_f32_16x16x32_bf16 v[14:17], v[156:159], v[212:215], v[14:17]
	v_mfma_f32_16x16x32_bf16 v[10:13], v[164:167], v[212:215], v[10:13]
	s_setprio 0
	s_setprio 1
	v_mfma_f32_16x16x32_bf16 v[54:57], v[168:171], v[184:187], v[54:57]
	v_mfma_f32_16x16x32_bf16 v[50:53], v[176:179], v[184:187], v[50:53]
	v_mfma_f32_16x16x32_bf16 v[38:41], v[168:171], v[192:195], v[38:41]
	v_mfma_f32_16x16x32_bf16 v[34:37], v[176:179], v[192:195], v[34:37]
	v_mfma_f32_16x16x32_bf16 v[22:25], v[168:171], v[200:203], v[22:25]
	v_mfma_f32_16x16x32_bf16 v[18:21], v[176:179], v[200:203], v[18:21]
	v_mfma_f32_16x16x32_bf16 v[6:9], v[168:171], v[208:211], v[6:9]
	v_mfma_f32_16x16x32_bf16 v[2:5], v[176:179], v[208:211], v[2:5]
	v_mfma_f32_16x16x32_bf16 v[54:57], v[172:175], v[188:191], v[54:57]
	v_mfma_f32_16x16x32_bf16 v[50:53], v[180:183], v[188:191], v[50:53]
	v_mfma_f32_16x16x32_bf16 v[38:41], v[172:175], v[196:199], v[38:41]
	v_mfma_f32_16x16x32_bf16 v[34:37], v[180:183], v[196:199], v[34:37]
	v_mfma_f32_16x16x32_bf16 v[22:25], v[172:175], v[204:207], v[22:25]
	v_mfma_f32_16x16x32_bf16 v[18:21], v[180:183], v[204:207], v[18:21]
	v_mfma_f32_16x16x32_bf16 v[6:9], v[172:175], v[212:215], v[6:9]
	v_mfma_f32_16x16x32_bf16 v[2:5], v[180:183], v[212:215], v[2:5]
	s_setprio 0
	s_barrier
	s_add_i32 s48, s48, 2
	s_add_u32 s36, s36, 0x100
	s_addc_u32 s37, s37, 0
	s_add_u32 s34, s34, 0x100
	s_addc_u32 s35, s35, 0
	s_cmp_gt_u32 s48, 13
	s_cbranch_scc0 .LBB0_1628
	s_and_b64 vcc, exec, s[18:19]
	s_cbranch_vccz .LBB0_1631
	s_barrier

; #define PG8_STAGE(bufoff, gbase, voff) do { _Pragma("unroll") for (int _i = 0; _i < 2; ++_i) \
;         __builtin_amdgcn_global_load_lds((const unsigned*)((const char*)(gbase) + (voff)[_i]), (PG8_LAS unsigned*)(lds + (bufoff) + ldsw + _i * 8192), 16, 0, 0); } while (0)
; #define PG8_LDA(dst, b, h) do { _Pragma("unroll") for (int m = 0; m < 4; ++m) _Pragma("unroll") for (int k = 0; k < 2; ++k) dst[m][k] = *(const PG8_LAS bf16x8*)(lds + PG8_SA(b, h) + aoff + m * 2048 + k * 1024); } while (0)
; #define PG8_LDB(dst, b, h) do { _Pragma("unroll") for (int n = 0; n < 2; ++n) _Pragma("unroll") for (int k = 0; k < 2; ++k) dst[n][k] = *(const PG8_LAS bf16x8*)(lds + PG8_SB(b, h) + boff + n * 2048 + k * 1024); } while (0)
; #define PG8_MMA(ai, bj, At, Bt) do { __builtin_amdgcn_s_setprio(1); _Pragma("unroll") for (int m = 0; m < 4; ++m) _Pragma("unroll") for (int n = 0; n < 2; ++n) _Pragma("unroll") for (int k = 0; k < 2; ++k) \
;         acc[ai][bj][m][n] = __builtin_amdgcn_mfma_f32_16x16x32_bf16(Bt[n][k], At[m][k], acc[ai][bj][m][n], 0, 0, 0); __builtin_amdgcn_s_setprio(0); } while (0)
; #define PG8_WAIT_V(n) asm volatile("s_waitcnt vmcnt(" #n ")" ::: "memory")
; #define PG8_WAIT_L(n) asm volatile("s_waitcnt lgkmcnt(" #n ")" ::: "memory")
; template <class Epi, class Sched, bool ALIGN_EPI = false, bool SP2 = false>
; __device__ __forceinline__ void gemm_phase(PG8_LAS unsigned char* lds, const Gemm g, const Sched& S, const Epi& E) {
;     ...
;             const bool last = (t == nt - 2);
;             const char* a1 = cA + (size_t)(t + 1) * kstep;
;             const char* a2 = last ? nA : cA + (size_t)(t + 2) * kstep; const char* b2 = last ? nB : cB + (size_t)(t + 2) * kstep;
;             const char* a3 = a2 + kstep; const char* b3 = b2 + kstep;
;             if (last && has_next) S.a_ready(nxt);
;             if constexpr (SP2) {
;             PG8_LDB(B0, 0, 0); PG8_LDB(B1, 0, 1); PG8_SCHED; PG8_LDA(At, 0, 0); PG8_STAGE(PG8_SA(1, 1), a1 + hstep, voffA);
;             PG8_WAIT_V(8); PG8_WAIT_L(0); PG8_BAR; PG8_MMA(0, 0, At, B0); PG8_MMA(0, 1, At, B1); PG8_BAR; PG8_SCHED;
;             PG8_LDA(At, 0, 1); PG8_STAGE(PG8_SB(0, 0), b2, voffB); PG8_STAGE(PG8_SB(0, 1), b2 + hstep, voffB); PG8_STAGE(PG8_SA(0, 0), a2, voffA);
;             PG8_WAIT_V(8); PG8_WAIT_L(0); PG8_BAR; PG8_MMA(1, 0, At, B0); PG8_MMA(1, 1, At, B1); PG8_BAR; PG8_SCHED;
.LBB0_1706:
	v_add_u32_e32 v162, s39, v152
	ds_read_b128 v[154:157], v162
	ds_read_b128 v[158:161], v162 offset:1024
	ds_read_b128 v[166:169], v162 offset:2048
	ds_read_b128 v[170:173], v162 offset:3072
	v_add_u32_e32 v162, s40, v152
	s_add_u32 s2, s14, s20
	ds_read_b128 v[174:177], v162
	ds_read_b128 v[178:181], v162 offset:1024
	ds_read_b128 v[182:185], v162 offset:2048
	ds_read_b128 v[186:189], v162 offset:3072
	s_addc_u32 s3, s15, s21
	s_add_u32 s2, s2, 0x100
	s_addc_u32 s3, s3, 0
	s_add_u32 s47, s44, s20
	s_addc_u32 s48, s45, s21
	s_cmpk_eq_i32 s20, 0x1500
	s_cselect_b32 s23, s19, s3
	s_cselect_b32 s22, s18, s2
	s_cselect_b32 s3, s7, s48
	s_cselect_b32 s2, s6, s47
	v_lshl_add_u64 v[162:163], v[146:147], 0, s[20:21]
	s_add_i32 m0, s30, 0xc000
	ds_read_b128 v[190:193], v153
	ds_read_b128 v[194:197], v153 offset:1024
	ds_read_b128 v[198:201], v153 offset:2048
	ds_read_b128 v[202:205], v153 offset:3072
	ds_read_b128 v[206:209], v153 offset:4096
	ds_read_b128 v[210:213], v153 offset:5120
	ds_read_b128 v[214:217], v153 offset:6144
	ds_read_b128 v[218:221], v153 offset:7168
	global_load_lds_dwordx4 v[162:163], off
	v_lshl_add_u64 v[162:163], v[148:149], 0, s[20:21]
	s_add_i32 m0, s30, 0xe000
	s_nop 0
	global_load_lds_dwordx4 v[162:163], off
	s_waitcnt vmcnt(8)
	s_waitcnt lgkmcnt(0)
	v_mfma_f32_16x16x32_bf16 v[70:73], v[154:157], v[190:193], v[70:73]
	v_mfma_f32_16x16x32_bf16 v[78:81], v[166:169], v[190:193], v[78:81]
	v_mfma_f32_16x16x32_bf16 v[94:97], v[154:157], v[198:201], v[94:97]
	v_mfma_f32_16x16x32_bf16 v[118:121], v[166:169], v[198:201], v[118:121]
	v_mfma_f32_16x16x32_bf16 v[106:109], v[154:157], v[206:209], v[106:109]
	v_mfma_f32_16x16x32_bf16 v[114:117], v[166:169], v[206:209], v[114:117]
	v_mfma_f32_16x16x32_bf16 v[122:125], v[154:157], v[214:217], v[122:125]
	v_mfma_f32_16x16x32_bf16 v[126:129], v[166:169], v[214:217], v[126:129]
	s_barrier
	s_setprio 1
	s_waitcnt lgkmcnt(0)
	v_mfma_f32_16x16x32_bf16 v[70:73], v[158:161], v[194:197], v[70:73]
	v_mfma_f32_16x16x32_bf16 v[78:81], v[170:173], v[194:197], v[78:81]
	v_mfma_f32_16x16x32_bf16 v[94:97], v[158:161], v[202:205], v[94:97]
	v_mfma_f32_16x16x32_bf16 v[118:121], v[170:173], v[202:205], v[118:121]
	v_mfma_f32_16x16x32_bf16 v[106:109], v[158:161], v[210:213], v[106:109]
	v_mfma_f32_16x16x32_bf16 v[114:117], v[170:173], v[210:213], v[114:117]
	v_mfma_f32_16x16x32_bf16 v[122:125], v[158:161], v[218:221], v[122:125]
	v_mfma_f32_16x16x32_bf16 v[126:129], v[170:173], v[218:221], v[126:129]
	s_setprio 0
	s_setprio 1
	v_mfma_f32_16x16x32_bf16 v[66:69], v[174:177], v[190:193], v[66:69]
	v_mfma_f32_16x16x32_bf16 v[74:77], v[182:185], v[190:193], v[74:77]
	v_mfma_f32_16x16x32_bf16 v[82:85], v[174:177], v[198:201], v[82:85]
	v_mfma_f32_16x16x32_bf16 v[86:89], v[182:185], v[198:201], v[86:89]
	v_mfma_f32_16x16x32_bf16 v[90:93], v[174:177], v[206:209], v[90:93]
	v_mfma_f32_16x16x32_bf16 v[98:101], v[182:185], v[206:209], v[98:101]
	v_mfma_f32_16x16x32_bf16 v[102:105], v[174:177], v[214:217], v[102:105]
	v_mfma_f32_16x16x32_bf16 v[110:113], v[182:185], v[214:217], v[110:113]
	v_mfma_f32_16x16x32_bf16 v[66:69], v[178:181], v[194:197], v[66:69]
	v_mfma_f32_16x16x32_bf16 v[74:77], v[186:189], v[194:197], v[74:77]
	v_mfma_f32_16x16x32_bf16 v[82:85], v[178:181], v[202:205], v[82:85]
	v_mfma_f32_16x16x32_bf16 v[86:89], v[186:189], v[202:205], v[86:89]
	v_mfma_f32_16x16x32_bf16 v[90:93], v[178:181], v[210:213], v[90:93]
	v_mfma_f32_16x16x32_bf16 v[98:101], v[186:189], v[210:213], v[98:101]
	v_mfma_f32_16x16x32_bf16 v[102:105], v[178:181], v[218:221], v[102:105]
	v_mfma_f32_16x16x32_bf16 v[110:113], v[186:189], v[218:221], v[110:113]
	s_setprio 0
	s_barrier
	s_add_i32 s47, s39, s29
	v_lshl_add_u64 v[162:163], s[2:3], 0, v[132:133]
	s_mov_b32 m0, s47
	ds_read_b128 v[190:193], v153 offset:16384
	ds_read_b128 v[194:197], v153 offset:17408
	ds_read_b128 v[198:201], v153 offset:18432
	ds_read_b128 v[202:205], v153 offset:19456
	ds_read_b128 v[206:209], v153 offset:20480
	ds_read_b128 v[210:213], v153 offset:21504
	ds_read_b128 v[214:217], v153 offset:22528
	ds_read_b128 v[218:221], v153 offset:23552
	global_load_lds_dwordx4 v[162:163], off
	s_add_i32 m0, s47, 0x2000
	s_add_u32 s48, s2, 0xb0000
	v_lshl_add_u64 v[222:223], s[2:3], 0, v[136:137]
	s_addc_u32 s49, s3, 0
	s_add_i32 s47, s40, s29
	global_load_lds_dwordx4 v[222:223], off
	v_lshl_add_u64 v[224:225], s[48:49], 0, v[132:133]
	s_mov_b32 m0, s47
	v_lshl_add_u64 v[226:227], s[22:23], 0, v[134:135]
	global_load_lds_dwordx4 v[224:225], off
	v_lshl_add_u64 v[224:225], s[48:49], 0, v[136:137]
	s_add_i32 m0, s47, 0x2000
	s_nop 0
	global_load_lds_dwordx4 v[224:225], off
	v_lshl_add_u64 v[224:225], s[22:23], 0, v[130:131]
	s_mov_b32 m0, s30
	s_nop 0
	global_load_lds_dwordx4 v[224:225], off
	s_mov_b32 m0, s31
	s_nop 0
	global_load_lds_dwordx4 v[226:227], off
	s_waitcnt vmcnt(8)
	s_waitcnt lgkmcnt(0)
	v_mfma_f32_16x16x32_bf16 v[62:65], v[154:157], v[190:193], v[62:65]
	v_mfma_f32_16x16x32_bf16 v[58:61], v[166:169], v[190:193], v[58:61]
	v_mfma_f32_16x16x32_bf16 v[46:49], v[154:157], v[198:201], v[46:49]
	v_mfma_f32_16x16x32_bf16 v[42:45], v[166:169], v[198:201], v[42:45]
	v_mfma_f32_16x16x32_bf16 v[30:33], v[154:157], v[206:209], v[30:33]
	v_mfma_f32_16x16x32_bf16 v[26:29], v[166:169], v[206:209], v[26:29]
	v_mfma_f32_16x16x32_bf16 v[14:17], v[154:157], v[214:217], v[14:17]
	v_mfma_f32_16x16x32_bf16 v[10:13], v[166:169], v[214:217], v[10:13]
	s_barrier
; #define PG8_STAGE(bufoff, gbase, voff) do { _Pragma("unroll") for (int _i = 0; _i < 2; ++_i) \
;         __builtin_amdgcn_global_load_lds((const unsigned*)((const char*)(gbase) + (voff)[_i]), (PG8_LAS unsigned*)(lds + (bufoff) + ldsw + _i * 8192), 16, 0, 0); } while (0)
; #define PG8_LDA(dst, b, h) do { _Pragma("unroll") for (int m = 0; m < 4; ++m) _Pragma("unroll") for (int k = 0; k < 2; ++k) dst[m][k] = *(const PG8_LAS bf16x8*)(lds + PG8_SA(b, h) + aoff + m * 2048 + k * 1024); } while (0)
; #define PG8_LDB(dst, b, h) do { _Pragma("unroll") for (int n = 0; n < 2; ++n) _Pragma("unroll") for (int k = 0; k < 2; ++k) dst[n][k] = *(const PG8_LAS bf16x8*)(lds + PG8_SB(b, h) + boff + n * 2048 + k * 1024); } while (0)
; #define PG8_MMA(ai, bj, At, Bt) do { __builtin_amdgcn_s_setprio(1); _Pragma("unroll") for (int m = 0; m < 4; ++m) _Pragma("unroll") for (int n = 0; n < 2; ++n) _Pragma("unroll") for (int k = 0; k < 2; ++k) \
;         acc[ai][bj][m][n] = __builtin_amdgcn_mfma_f32_16x16x32_bf16(Bt[n][k], At[m][k], acc[ai][bj][m][n], 0, 0, 0); __builtin_amdgcn_s_setprio(0); } while (0)
; #define PG8_WAIT_V(n) asm volatile("s_waitcnt vmcnt(" #n ")" ::: "memory")
; #define PG8_WAIT_L(n) asm volatile("s_waitcnt lgkmcnt(" #n ")" ::: "memory")
; #define PG8_BAR __builtin_amdgcn_s_barrier()
; #define PG8_SCHED __builtin_amdgcn_sched_barrier(0)
; template <class Epi, class Sched, bool ALIGN_EPI = false, bool SP2 = false>
; __device__ __forceinline__ void gemm_phase(PG8_LAS unsigned char* lds, const Gemm g, const Sched& S, const Epi& E) {
;     ...
;             PG8_WAIT_V(8); PG8_WAIT_L(0); PG8_BAR; PG8_MMA(1, 0, At, B0); PG8_MMA(1, 1, At, B1); PG8_BAR; PG8_SCHED;
;             PG8_LDB(B0, 1, 0); PG8_LDB(B1, 1, 1); PG8_SCHED; PG8_LDA(At, 1, 0); PG8_STAGE(PG8_SA(0, 1), a2 + hstep, voffA);
;             PG8_WAIT_V(8); PG8_WAIT_L(0); PG8_BAR; PG8_MMA(0, 0, At, B0); PG8_MMA(0, 1, At, B1); PG8_BAR; PG8_SCHED;
	s_setprio 1
	s_waitcnt lgkmcnt(0)
	v_mfma_f32_16x16x32_bf16 v[62:65], v[158:161], v[194:197], v[62:65]
	v_mfma_f32_16x16x32_bf16 v[58:61], v[170:173], v[194:197], v[58:61]
	v_mfma_f32_16x16x32_bf16 v[46:49], v[158:161], v[202:205], v[46:49]
	v_mfma_f32_16x16x32_bf16 v[42:45], v[170:173], v[202:205], v[42:45]
	v_mfma_f32_16x16x32_bf16 v[30:33], v[158:161], v[210:213], v[30:33]
	v_mfma_f32_16x16x32_bf16 v[26:29], v[170:173], v[210:213], v[26:29]
	v_mfma_f32_16x16x32_bf16 v[14:17], v[158:161], v[218:221], v[14:17]
	v_mfma_f32_16x16x32_bf16 v[10:13], v[170:173], v[218:221], v[10:13]
	s_setprio 0
	s_setprio 1
	v_mfma_f32_16x16x32_bf16 v[54:57], v[174:177], v[190:193], v[54:57]
	v_mfma_f32_16x16x32_bf16 v[50:53], v[182:185], v[190:193], v[50:53]
	v_mfma_f32_16x16x32_bf16 v[38:41], v[174:177], v[198:201], v[38:41]
	v_mfma_f32_16x16x32_bf16 v[34:37], v[182:185], v[198:201], v[34:37]
	v_mfma_f32_16x16x32_bf16 v[22:25], v[174:177], v[206:209], v[22:25]
	v_mfma_f32_16x16x32_bf16 v[18:21], v[182:185], v[206:209], v[18:21]
	v_mfma_f32_16x16x32_bf16 v[6:9], v[174:177], v[214:217], v[6:9]
	v_mfma_f32_16x16x32_bf16 v[2:5], v[182:185], v[214:217], v[2:5]
	v_mfma_f32_16x16x32_bf16 v[54:57], v[178:181], v[194:197], v[54:57]
	v_mfma_f32_16x16x32_bf16 v[50:53], v[186:189], v[194:197], v[50:53]
	v_mfma_f32_16x16x32_bf16 v[38:41], v[178:181], v[202:205], v[38:41]
	v_mfma_f32_16x16x32_bf16 v[34:37], v[186:189], v[202:205], v[34:37]
	v_mfma_f32_16x16x32_bf16 v[22:25], v[178:181], v[210:213], v[22:25]
	v_mfma_f32_16x16x32_bf16 v[18:21], v[186:189], v[210:213], v[18:21]
	v_mfma_f32_16x16x32_bf16 v[6:9], v[178:181], v[218:221], v[6:9]
	v_mfma_f32_16x16x32_bf16 v[2:5], v[186:189], v[218:221], v[2:5]
	s_setprio 0
	s_barrier
	s_add_i32 s47, 0, 0x18000
	v_add_u32_e32 v165, s47, v152
	s_add_i32 s48, 0, 0x1c000
	ds_read_b128 v[154:157], v165
	ds_read_b128 v[158:161], v165 offset:1024
	ds_read_b128 v[166:169], v165 offset:2048
	ds_read_b128 v[170:173], v165 offset:3072
	v_add_u32_e32 v165, s48, v152
	ds_read_b128 v[174:177], v165
	ds_read_b128 v[178:181], v165 offset:1024
	ds_read_b128 v[182:185], v165 offset:2048
	ds_read_b128 v[186:189], v165 offset:3072
	s_add_u32 s22, s22, 0xb0000
	s_addc_u32 s23, s23, 0
	s_mov_b32 m0, s33
	v_lshl_add_u64 v[228:229], s[22:23], 0, v[130:131]
	ds_read_b128 v[190:193], v153 offset:32768
	ds_read_b128 v[194:197], v153 offset:33792
	ds_read_b128 v[198:201], v153 offset:34816
	ds_read_b128 v[202:205], v153 offset:35840
	ds_read_b128 v[206:209], v153 offset:36864
	ds_read_b128 v[210:213], v153 offset:37888
	ds_read_b128 v[214:217], v153 offset:38912
	ds_read_b128 v[218:221], v153 offset:39936
	global_load_lds_dwordx4 v[228:229], off
	v_lshl_add_u64 v[228:229], s[22:23], 0, v[134:135]
	s_mov_b32 m0, s34
	s_nop 0
	global_load_lds_dwordx4 v[228:229], off
	s_waitcnt vmcnt(8)
	s_waitcnt lgkmcnt(0)
	v_mfma_f32_16x16x32_bf16 v[70:73], v[154:157], v[190:193], v[70:73]
	v_mfma_f32_16x16x32_bf16 v[78:81], v[166:169], v[190:193], v[78:81]
	v_mfma_f32_16x16x32_bf16 v[94:97], v[154:157], v[198:201], v[94:97]
	v_mfma_f32_16x16x32_bf16 v[118:121], v[166:169], v[198:201], v[118:121]
	v_mfma_f32_16x16x32_bf16 v[106:109], v[154:157], v[206:209], v[106:109]
	v_mfma_f32_16x16x32_bf16 v[114:117], v[166:169], v[206:209], v[114:117]
	v_mfma_f32_16x16x32_bf16 v[122:125], v[154:157], v[214:217], v[122:125]
	v_mfma_f32_16x16x32_bf16 v[126:129], v[166:169], v[214:217], v[126:129]
	s_barrier
	s_setprio 1
	s_waitcnt lgkmcnt(0)
	v_mfma_f32_16x16x32_bf16 v[70:73], v[158:161], v[194:197], v[70:73]
	v_mfma_f32_16x16x32_bf16 v[78:81], v[170:173], v[194:197], v[78:81]
	v_mfma_f32_16x16x32_bf16 v[94:97], v[158:161], v[202:205], v[94:97]
	v_mfma_f32_16x16x32_bf16 v[118:121], v[170:173], v[202:205], v[118:121]
	v_mfma_f32_16x16x32_bf16 v[106:109], v[158:161], v[210:213], v[106:109]
	v_mfma_f32_16x16x32_bf16 v[114:117], v[170:173], v[210:213], v[114:117]
	v_mfma_f32_16x16x32_bf16 v[122:125], v[158:161], v[218:221], v[122:125]
	v_mfma_f32_16x16x32_bf16 v[126:129], v[170:173], v[218:221], v[126:129]
	s_setprio 0
	s_setprio 1
	v_mfma_f32_16x16x32_bf16 v[66:69], v[174:177], v[190:193], v[66:69]
	v_mfma_f32_16x16x32_bf16 v[74:77], v[182:185], v[190:193], v[74:77]
	v_mfma_f32_16x16x32_bf16 v[82:85], v[174:177], v[198:201], v[82:85]
	v_mfma_f32_16x16x32_bf16 v[86:89], v[182:185], v[198:201], v[86:89]
	v_mfma_f32_16x16x32_bf16 v[90:93], v[174:177], v[206:209], v[90:93]
	v_mfma_f32_16x16x32_bf16 v[98:101], v[182:185], v[206:209], v[98:101]
	v_mfma_f32_16x16x32_bf16 v[102:105], v[174:177], v[214:217], v[102:105]
	v_mfma_f32_16x16x32_bf16 v[110:113], v[182:185], v[214:217], v[110:113]
	v_mfma_f32_16x16x32_bf16 v[66:69], v[178:181], v[194:197], v[66:69]
	v_mfma_f32_16x16x32_bf16 v[74:77], v[186:189], v[194:197], v[74:77]
	v_mfma_f32_16x16x32_bf16 v[82:85], v[178:181], v[202:205], v[82:85]
	v_mfma_f32_16x16x32_bf16 v[86:89], v[186:189], v[202:205], v[86:89]
	v_mfma_f32_16x16x32_bf16 v[90:93], v[178:181], v[210:213], v[90:93]
	v_mfma_f32_16x16x32_bf16 v[98:101], v[186:189], v[210:213], v[98:101]
	v_mfma_f32_16x16x32_bf16 v[102:105], v[178:181], v[218:221], v[102:105]
	v_mfma_f32_16x16x32_bf16 v[110:113], v[186:189], v[218:221], v[110:113]
	s_setprio 0
	s_barrier
; #define PG8_STAGE(bufoff, gbase, voff) do { _Pragma("unroll") for (int _i = 0; _i < 2; ++_i) \
;         __builtin_amdgcn_global_load_lds((const unsigned*)((const char*)(gbase) + (voff)[_i]), (PG8_LAS unsigned*)(lds + (bufoff) + ldsw + _i * 8192), 16, 0, 0); } while (0)
; #define PG8_LDA(dst, b, h) do { _Pragma("unroll") for (int m = 0; m < 4; ++m) _Pragma("unroll") for (int k = 0; k < 2; ++k) dst[m][k] = *(const PG8_LAS bf16x8*)(lds + PG8_SA(b, h) + aoff + m * 2048 + k * 1024); } while (0)
; #define PG8_MMA(ai, bj, At, Bt) do { __builtin_amdgcn_s_setprio(1); _Pragma("unroll") for (int m = 0; m < 4; ++m) _Pragma("unroll") for (int n = 0; n < 2; ++n) _Pragma("unroll") for (int k = 0; k < 2; ++k) \
;         acc[ai][bj][m][n] = __builtin_amdgcn_mfma_f32_16x16x32_bf16(Bt[n][k], At[m][k], acc[ai][bj][m][n], 0, 0, 0); __builtin_amdgcn_s_setprio(0); } while (0)
; #define PG8_WAIT_V(n) asm volatile("s_waitcnt vmcnt(" #n ")" ::: "memory")
; #define PG8_WAIT_L(n) asm volatile("s_waitcnt lgkmcnt(" #n ")" ::: "memory")
; #define PG8_BAR __builtin_amdgcn_s_barrier()
; #define PG8_SCHED __builtin_amdgcn_sched_barrier(0)
; template <class Epi, class Sched, bool ALIGN_EPI = false, bool SP2 = false>
; __device__ __forceinline__ void gemm_phase(PG8_LAS unsigned char* lds, const Gemm g, const Sched& S, const Epi& E) {
;     ...
;             PG8_LDA(At, 1, 1); PG8_STAGE(PG8_SB(1, 0), b3, voffB); PG8_STAGE(PG8_SB(1, 1), b3 + hstep, voffB); PG8_STAGE(PG8_SA(1, 0), a3, voffA);
;             PG8_WAIT_V(8); PG8_WAIT_L(0); PG8_BAR; PG8_MMA(1, 0, At, B0); PG8_MMA(1, 1, At, B1); PG8_BAR; PG8_SCHED;
;     ...
;         if (!has_next) break;
; #pragma unroll
;         for (int a = 0; a < 2; ++a)
; #pragma unroll
;             for (int b = 0; b < 2; ++b)
; #pragma unroll
;                 for (int m = 0; m < 4; ++m)
; #pragma unroll
;                     for (int n = 0; n < 2; ++n) acc[a][b][m][n] = (f32x4){0.f, 0.f, 0.f, 0.f};
;         cur = nxt; cA = nA; cB = nB; ++ui;
	s_add_i32 s22, s47, s29
	v_lshl_add_u64 v[162:163], v[162:163], 0, s[16:17]
	s_mov_b32 m0, s22
	ds_read_b128 v[190:193], v153 offset:49152
	ds_read_b128 v[194:197], v153 offset:50176
	ds_read_b128 v[198:201], v153 offset:51200
	ds_read_b128 v[202:205], v153 offset:52224
	ds_read_b128 v[206:209], v153 offset:53248
	ds_read_b128 v[210:213], v153 offset:54272
	ds_read_b128 v[214:217], v153 offset:55296
	ds_read_b128 v[218:221], v153 offset:56320
	global_load_lds_dwordx4 v[162:163], off
	s_add_i32 m0, s22, 0x2000
	s_add_u32 s2, s2, 0xb0080
	v_lshl_add_u64 v[162:163], v[222:223], 0, s[16:17]
	s_addc_u32 s3, s3, 0
	s_add_i32 s22, s48, s29
	global_load_lds_dwordx4 v[162:163], off
	v_lshl_add_u64 v[162:163], s[2:3], 0, v[132:133]
	s_mov_b32 m0, s22
	s_nop 0
	global_load_lds_dwordx4 v[162:163], off
	v_lshl_add_u64 v[162:163], s[2:3], 0, v[136:137]
	s_add_i32 m0, s22, 0x2000
	s_nop 0
	global_load_lds_dwordx4 v[162:163], off
	v_lshl_add_u64 v[162:163], v[224:225], 0, s[16:17]
	s_mov_b32 m0, s37
	s_nop 0
	global_load_lds_dwordx4 v[162:163], off
	v_lshl_add_u64 v[162:163], v[226:227], 0, s[16:17]
	s_mov_b32 m0, s38
	s_nop 0
	global_load_lds_dwordx4 v[162:163], off
	s_waitcnt vmcnt(8)
	s_waitcnt lgkmcnt(0)
	v_mfma_f32_16x16x32_bf16 v[62:65], v[154:157], v[190:193], v[62:65]
	v_mfma_f32_16x16x32_bf16 v[58:61], v[166:169], v[190:193], v[58:61]
	v_mfma_f32_16x16x32_bf16 v[46:49], v[154:157], v[198:201], v[46:49]
	v_mfma_f32_16x16x32_bf16 v[42:45], v[166:169], v[198:201], v[42:45]
	v_mfma_f32_16x16x32_bf16 v[30:33], v[154:157], v[206:209], v[30:33]
	v_mfma_f32_16x16x32_bf16 v[26:29], v[166:169], v[206:209], v[26:29]
	v_mfma_f32_16x16x32_bf16 v[14:17], v[154:157], v[214:217], v[14:17]
	v_mfma_f32_16x16x32_bf16 v[10:13], v[166:169], v[214:217], v[10:13]
	s_barrier
	s_setprio 1
	s_waitcnt lgkmcnt(0)
	v_mfma_f32_16x16x32_bf16 v[62:65], v[158:161], v[194:197], v[62:65]
	v_mfma_f32_16x16x32_bf16 v[58:61], v[170:173], v[194:197], v[58:61]
	v_mfma_f32_16x16x32_bf16 v[46:49], v[158:161], v[202:205], v[46:49]
	v_mfma_f32_16x16x32_bf16 v[42:45], v[170:173], v[202:205], v[42:45]
	v_mfma_f32_16x16x32_bf16 v[30:33], v[158:161], v[210:213], v[30:33]
	v_mfma_f32_16x16x32_bf16 v[26:29], v[170:173], v[210:213], v[26:29]
	v_mfma_f32_16x16x32_bf16 v[14:17], v[158:161], v[218:221], v[14:17]
	v_mfma_f32_16x16x32_bf16 v[10:13], v[170:173], v[218:221], v[10:13]
	s_setprio 0
	s_setprio 1
	v_mfma_f32_16x16x32_bf16 v[54:57], v[174:177], v[190:193], v[54:57]
	v_mfma_f32_16x16x32_bf16 v[50:53], v[182:185], v[190:193], v[50:53]
	v_mfma_f32_16x16x32_bf16 v[38:41], v[174:177], v[198:201], v[38:41]
	v_mfma_f32_16x16x32_bf16 v[34:37], v[182:185], v[198:201], v[34:37]
	v_mfma_f32_16x16x32_bf16 v[22:25], v[174:177], v[206:209], v[22:25]
	v_mfma_f32_16x16x32_bf16 v[18:21], v[182:185], v[206:209], v[18:21]
	v_mfma_f32_16x16x32_bf16 v[6:9], v[174:177], v[214:217], v[6:9]
	v_mfma_f32_16x16x32_bf16 v[2:5], v[182:185], v[214:217], v[2:5]
	v_mfma_f32_16x16x32_bf16 v[54:57], v[178:181], v[194:197], v[54:57]
	v_mfma_f32_16x16x32_bf16 v[50:53], v[186:189], v[194:197], v[50:53]
	v_mfma_f32_16x16x32_bf16 v[38:41], v[178:181], v[202:205], v[38:41]
	v_mfma_f32_16x16x32_bf16 v[34:37], v[186:189], v[202:205], v[34:37]
	v_mfma_f32_16x16x32_bf16 v[22:25], v[178:181], v[210:213], v[22:25]
	v_mfma_f32_16x16x32_bf16 v[18:21], v[186:189], v[210:213], v[18:21]
	v_mfma_f32_16x16x32_bf16 v[6:9], v[178:181], v[218:221], v[6:9]
	v_mfma_f32_16x16x32_bf16 v[2:5], v[186:189], v[218:221], v[2:5]
	s_setprio 0
	s_barrier
	s_add_i32 s46, s46, 2
	s_add_u32 s20, s20, 0x100
	s_addc_u32 s21, s21, 0
	s_cmp_gt_u32 s46, 41
	s_cbranch_scc0 .LBB0_1706
	s_add_u32 s2, s44, 0xffffff00
	s_addc_u32 s3, s45, -1
	s_and_b64 vcc, exec, s[4:5]
	s_cbranch_vccnz .LBB0_1709
	v_mov_b32_e32 v2, 0
	s_mov_b32 s12, s41
	s_mov_b32 s25, s42
	s_mov_b64 s[14:15], s[18:19]
	s_mov_b32 s36, s43
	v_mov_b32_e32 v3, v2
	v_mov_b64_e32 v[4:5], v[2:3]
	v_mov_b64_e32 v[6:7], v[2:3]
	v_mov_b64_e32 v[8:9], v[2:3]
	v_mov_b64_e32 v[18:19], v[2:3]
	v_mov_b64_e32 v[20:21], v[2:3]
	v_mov_b64_e32 v[22:23], v[2:3]
	v_mov_b64_e32 v[24:25], v[2:3]
	v_mov_b64_e32 v[34:35], v[2:3]
	v_mov_b64_e32 v[36:37], v[2:3]
	v_mov_b64_e32 v[38:39], v[2:3]
	v_mov_b64_e32 v[40:41], v[2:3]
	v_mov_b64_e32 v[50:51], v[2:3]
	v_mov_b64_e32 v[52:53], v[2:3]
	v_mov_b64_e32 v[54:55], v[2:3]
	v_mov_b64_e32 v[56:57], v[2:3]
	v_mov_b64_e32 v[10:11], v[2:3]
	v_mov_b64_e32 v[12:13], v[2:3]
	v_mov_b64_e32 v[14:15], v[2:3]
	v_mov_b64_e32 v[16:17], v[2:3]
	v_mov_b64_e32 v[26:27], v[2:3]
	v_mov_b64_e32 v[28:29], v[2:3]
	v_mov_b64_e32 v[30:31], v[2:3]
	v_mov_b64_e32 v[32:33], v[2:3]
	v_mov_b64_e32 v[42:43], v[2:3]
	v_mov_b64_e32 v[44:45], v[2:3]
	v_mov_b64_e32 v[46:47], v[2:3]
	v_mov_b64_e32 v[48:49], v[2:3]
	v_mov_b64_e32 v[58:59], v[2:3]
	v_mov_b64_e32 v[60:61], v[2:3]
	v_mov_b64_e32 v[62:63], v[2:3]
	v_mov_b64_e32 v[64:65], v[2:3]
	v_mov_b64_e32 v[110:111], v[2:3]
	v_mov_b64_e32 v[112:113], v[2:3]
	v_mov_b64_e32 v[102:103], v[2:3]
	v_mov_b64_e32 v[104:105], v[2:3]
	v_mov_b64_e32 v[98:99], v[2:3]
	v_mov_b64_e32 v[100:101], v[2:3]
	v_mov_b64_e32 v[90:91], v[2:3]
	v_mov_b64_e32 v[92:93], v[2:3]
	v_mov_b64_e32 v[86:87], v[2:3]
	v_mov_b64_e32 v[88:89], v[2:3]
	v_mov_b64_e32 v[82:83], v[2:3]
	v_mov_b64_e32 v[84:85], v[2:3]
	v_mov_b64_e32 v[74:75], v[2:3]
	v_mov_b64_e32 v[76:77], v[2:3]
	v_mov_b64_e32 v[66:67], v[2:3]
	v_mov_b64_e32 v[68:69], v[2:3]
	v_mov_b64_e32 v[126:127], v[2:3]
	v_mov_b64_e32 v[128:129], v[2:3]
	v_mov_b64_e32 v[122:123], v[2:3]
	v_mov_b64_e32 v[124:125], v[2:3]
	v_mov_b64_e32 v[114:115], v[2:3]
	v_mov_b64_e32 v[116:117], v[2:3]
	v_mov_b64_e32 v[106:107], v[2:3]
	v_mov_b64_e32 v[108:109], v[2:3]
	v_mov_b64_e32 v[118:119], v[2:3]
	v_mov_b64_e32 v[120:121], v[2:3]
	v_mov_b64_e32 v[94:95], v[2:3]
	v_mov_b64_e32 v[96:97], v[2:3]
	v_mov_b64_e32 v[78:79], v[2:3]
	v_mov_b64_e32 v[80:81], v[2:3]
	v_mov_b64_e32 v[70:71], v[2:3]
	v_mov_b64_e32 v[72:73], v[2:3]
	s_andn2_b64 vcc, exec, s[0:1]
	s_cbranch_vccnz .LBB0_1710
	s_branch .LBB0_1711
